# P1 x-modulate rows hand-written (16 consecutive rows per wave, loads three rows ahead, DPP reductions)
# speedup vs baseline: 1.0108x; 1.0016x over previous
.LBB0_155:
	s_or_b64 exec, exec, s[0:1]
	s_waitcnt lgkmcnt(0)
	v_mov_b32_e32 v0, v208
	v_readlane_b32 s0, v255, 4
	s_barrier
	s_lshl_b32 s60, s0, 3
	v_ashrrev_i32_e32 v1, 6, v0
	v_add_u32_e32 v28, s60, v1
	s_mov_b32 s10, 0x8000
	s_lshl_b32 s0, s48, 3
	v_cmp_gt_i32_e32 vcc, s10, v28
	v_mbcnt_lo_u32_b32 v246, -1, 0
	v_readlane_b32 s1, v255, 5
	s_and_saveexec_b64 s[2:3], vcc
	v_readlane_b32 s12, v255, 2
	v_readlane_b32 s13, v255, 3
	v_lshrrev_b32_e32 v112, 6, v208
	v_and_b32_e32 v113, 63, v208
	v_readfirstlane_b32 s14, v112
	v_lshlrev_b32_e32 v120, 4, v113
	v_lshlrev_b32_e32 v121, 3, v113
	s_nop 1
	s_add_u32 s1, s60, s14
	s_lshl_b32 s14, s1, 16
	s_add_u32 s4, s52, s14
	s_addc_u32 s5, s53, 0
	s_lshr_b32 s14, s14, 1
	s_add_u32 s6, s90, s14
	s_addc_u32 s7, s91, 0
	s_add_u32 s6, s6, 0x2400000
	s_addc_u32 s7, s7, 0
	s_lshr_b32 s14, s1, 7
	s_mul_i32 s14, s14, 0x3000
	s_add_u32 s8, s90, s14
	s_addc_u32 s9, s91, 0
	s_add_u32 s8, s8, 0x2180000
	s_addc_u32 s9, s9, 0
	s_add_u32 s10, s8, 0x1000
	s_addc_u32 s11, s9, 0
	global_load_dwordx4 v[0:3], v120, s[10:11] offset:0
	global_load_dwordx4 v[4:7], v120, s[10:11] offset:1024
	global_load_dwordx4 v[8:11], v120, s[10:11] offset:2048
	global_load_dwordx4 v[12:15], v120, s[10:11] offset:3072
	global_load_dwordx4 v[16:19], v120, s[8:9] offset:0
	global_load_dwordx4 v[20:23], v120, s[8:9] offset:1024
	global_load_dwordx4 v[24:27], v120, s[8:9] offset:2048
	global_load_dwordx4 v[28:31], v120, s[8:9] offset:3072
	v_mov_b32_e32 v116, 0xba800000
	v_mov_b32_e32 v117, 0xba800000
	v_mov_b32_e32 v122, 0x3a800000
	v_mov_b32_e32 v123, 0x358637bd
	global_load_dwordx4 v[32:35], v120, s[4:5] offset:0
	global_load_dwordx4 v[36:39], v120, s[4:5] offset:1024
	global_load_dwordx4 v[40:43], v120, s[4:5] offset:2048
	global_load_dwordx4 v[44:47], v120, s[4:5] offset:3072
	s_add_u32 s4, s4, 0x1000
	s_addc_u32 s5, s5, 0
	global_load_dwordx4 v[48:51], v120, s[4:5] offset:0
	global_load_dwordx4 v[52:55], v120, s[4:5] offset:1024
	global_load_dwordx4 v[56:59], v120, s[4:5] offset:2048
	global_load_dwordx4 v[60:63], v120, s[4:5] offset:3072
	s_add_u32 s4, s4, 0x1000
	s_addc_u32 s5, s5, 0
	global_load_dwordx4 v[64:67], v120, s[4:5] offset:0
	global_load_dwordx4 v[68:71], v120, s[4:5] offset:1024
	global_load_dwordx4 v[72:75], v120, s[4:5] offset:2048
	global_load_dwordx4 v[76:79], v120, s[4:5] offset:3072
	s_add_u32 s4, s4, 0x1000
	s_addc_u32 s5, s5, 0
	global_load_dwordx4 v[80:83], v120, s[4:5] offset:0
	global_load_dwordx4 v[84:87], v120, s[4:5] offset:1024
	global_load_dwordx4 v[88:91], v120, s[4:5] offset:2048
	global_load_dwordx4 v[92:95], v120, s[4:5] offset:3072
	s_add_u32 s4, s4, 0x1000
	s_addc_u32 s5, s5, 0
	s_waitcnt vmcnt(12)
	v_pk_add_f32 v[0:1], v[0:1], 1.0 op_sel_hi:[1,0]
	v_pk_add_f32 v[2:3], v[2:3], 1.0 op_sel_hi:[1,0]
	v_pk_add_f32 v[4:5], v[4:5], 1.0 op_sel_hi:[1,0]
	v_pk_add_f32 v[6:7], v[6:7], 1.0 op_sel_hi:[1,0]
	v_pk_add_f32 v[8:9], v[8:9], 1.0 op_sel_hi:[1,0]
	v_pk_add_f32 v[10:11], v[10:11], 1.0 op_sel_hi:[1,0]
	v_pk_add_f32 v[12:13], v[12:13], 1.0 op_sel_hi:[1,0]
	v_pk_add_f32 v[14:15], v[14:15], 1.0 op_sel_hi:[1,0]
	v_pk_add_f32 v[96:97], v[32:33], v[34:35]
	v_pk_add_f32 v[96:97], v[96:97], v[36:37]
	v_pk_add_f32 v[96:97], v[96:97], v[38:39]
	v_pk_add_f32 v[96:97], v[96:97], v[40:41]
	v_pk_add_f32 v[96:97], v[96:97], v[42:43]
	v_pk_add_f32 v[96:97], v[96:97], v[44:45]
	v_pk_add_f32 v[96:97], v[96:97], v[46:47]
	v_add_f32_e32 v114, v96, v97
	s_nop 1
	v_add_f32_dpp v112, v114, v114 quad_perm:[1,0,3,2] row_mask:0xf bank_mask:0xf
	s_nop 1
	v_add_f32_dpp v112, v112, v112 quad_perm:[2,3,0,1] row_mask:0xf bank_mask:0xf
	s_nop 1
	v_add_f32_dpp v112, v112, v112 row_half_mirror row_mask:0xf bank_mask:0xf
	s_nop 1
	v_add_f32_dpp v112, v112, v112 row_mirror row_mask:0xf bank_mask:0xf
	s_nop 1
	v_add_f32_dpp v112, v112, v112 row_bcast:15 row_mask:0xa bank_mask:0xf
	s_nop 1
	v_add_f32_dpp v112, v112, v112 row_bcast:31 row_mask:0xc bank_mask:0xf
	s_nop 1
	v_readlane_b32 s14, v112, 63
	s_nop 3
	s_mov_b32 s15, s14
	v_pk_fma_f32 v[32:33], s[14:15], v[116:117], v[32:33]
	v_pk_fma_f32 v[34:35], s[14:15], v[116:117], v[34:35]
	v_pk_fma_f32 v[36:37], s[14:15], v[116:117], v[36:37]
	v_pk_fma_f32 v[38:39], s[14:15], v[116:117], v[38:39]
	v_pk_fma_f32 v[40:41], s[14:15], v[116:117], v[40:41]
	v_pk_fma_f32 v[42:43], s[14:15], v[116:117], v[42:43]
	v_pk_fma_f32 v[44:45], s[14:15], v[116:117], v[44:45]
	v_pk_fma_f32 v[46:47], s[14:15], v[116:117], v[46:47]
	v_pk_mul_f32 v[96:97], v[32:33], v[32:33]
	v_pk_fma_f32 v[96:97], v[34:35], v[34:35], v[96:97]
	v_pk_fma_f32 v[96:97], v[36:37], v[36:37], v[96:97]
	v_pk_fma_f32 v[96:97], v[38:39], v[38:39], v[96:97]
	v_pk_fma_f32 v[96:97], v[40:41], v[40:41], v[96:97]
	v_pk_fma_f32 v[96:97], v[42:43], v[42:43], v[96:97]
	v_pk_fma_f32 v[96:97], v[44:45], v[44:45], v[96:97]
	v_pk_fma_f32 v[96:97], v[46:47], v[46:47], v[96:97]
	v_add_f32_e32 v114, v96, v97
	s_nop 1
	v_add_f32_dpp v112, v114, v114 quad_perm:[1,0,3,2] row_mask:0xf bank_mask:0xf
	s_nop 1
	v_add_f32_dpp v112, v112, v112 quad_perm:[2,3,0,1] row_mask:0xf bank_mask:0xf
	s_nop 1
	v_add_f32_dpp v112, v112, v112 row_half_mirror row_mask:0xf bank_mask:0xf
	s_nop 1
	v_add_f32_dpp v112, v112, v112 row_mirror row_mask:0xf bank_mask:0xf
	s_nop 1
	v_add_f32_dpp v112, v112, v112 row_bcast:15 row_mask:0xa bank_mask:0xf
	s_nop 1
	v_add_f32_dpp v112, v112, v112 row_bcast:31 row_mask:0xc bank_mask:0xf
	s_nop 1
	v_readlane_b32 s14, v112, 63
	s_nop 3
	v_fma_f32 v118, s14, v122, v123
	v_rsq_f32_e32 v118, v118
	s_nop 0
	v_pk_mul_f32 v[32:33], v[32:33], v[118:119] op_sel_hi:[1,0]
	v_pk_mul_f32 v[34:35], v[34:35], v[118:119] op_sel_hi:[1,0]
	v_pk_mul_f32 v[36:37], v[36:37], v[118:119] op_sel_hi:[1,0]
	v_pk_mul_f32 v[38:39], v[38:39], v[118:119] op_sel_hi:[1,0]
	v_pk_mul_f32 v[40:41], v[40:41], v[118:119] op_sel_hi:[1,0]
	v_pk_mul_f32 v[42:43], v[42:43], v[118:119] op_sel_hi:[1,0]
	v_pk_mul_f32 v[44:45], v[44:45], v[118:119] op_sel_hi:[1,0]
	v_pk_mul_f32 v[46:47], v[46:47], v[118:119] op_sel_hi:[1,0]
	v_pk_fma_f32 v[32:33], v[32:33], v[0:1], v[16:17]
	v_pk_fma_f32 v[34:35], v[34:35], v[2:3], v[18:19]
	v_pk_fma_f32 v[36:37], v[36:37], v[4:5], v[20:21]
	v_pk_fma_f32 v[38:39], v[38:39], v[6:7], v[22:23]
	v_pk_fma_f32 v[40:41], v[40:41], v[8:9], v[24:25]
	v_pk_fma_f32 v[42:43], v[42:43], v[10:11], v[26:27]
	v_pk_fma_f32 v[44:45], v[44:45], v[12:13], v[28:29]
	v_pk_fma_f32 v[46:47], v[46:47], v[14:15], v[30:31]
	v_cvt_pk_bf16_f32 v96, v32, v33
	v_cvt_pk_bf16_f32 v97, v34, v35
	v_cvt_pk_bf16_f32 v98, v36, v37
	v_cvt_pk_bf16_f32 v99, v38, v39
	v_cvt_pk_bf16_f32 v100, v40, v41
	v_cvt_pk_bf16_f32 v101, v42, v43
	v_cvt_pk_bf16_f32 v102, v44, v45
	v_cvt_pk_bf16_f32 v103, v46, v47
	global_store_dwordx2 v121, v[96:97], s[6:7] offset:0
	global_store_dwordx2 v121, v[98:99], s[6:7] offset:512
	global_store_dwordx2 v121, v[100:101], s[6:7] offset:1024
	global_store_dwordx2 v121, v[102:103], s[6:7] offset:1536
	s_add_u32 s6, s6, 0x800
	s_addc_u32 s7, s7, 0
	global_load_dwordx4 v[32:35], v120, s[4:5] offset:0
	global_load_dwordx4 v[36:39], v120, s[4:5] offset:1024
	global_load_dwordx4 v[40:43], v120, s[4:5] offset:2048
	global_load_dwordx4 v[44:47], v120, s[4:5] offset:3072
	s_add_u32 s4, s4, 0x1000
	s_addc_u32 s5, s5, 0
	s_waitcnt vmcnt(16)
	v_pk_add_f32 v[96:97], v[48:49], v[50:51]
	v_pk_add_f32 v[96:97], v[96:97], v[52:53]
	v_pk_add_f32 v[96:97], v[96:97], v[54:55]
	v_pk_add_f32 v[96:97], v[96:97], v[56:57]
	v_pk_add_f32 v[96:97], v[96:97], v[58:59]
	v_pk_add_f32 v[96:97], v[96:97], v[60:61]
	v_pk_add_f32 v[96:97], v[96:97], v[62:63]
	v_add_f32_e32 v114, v96, v97
	s_nop 1
	v_add_f32_dpp v112, v114, v114 quad_perm:[1,0,3,2] row_mask:0xf bank_mask:0xf
	s_nop 1
	v_add_f32_dpp v112, v112, v112 quad_perm:[2,3,0,1] row_mask:0xf bank_mask:0xf
	s_nop 1
	v_add_f32_dpp v112, v112, v112 row_half_mirror row_mask:0xf bank_mask:0xf
	s_nop 1
	v_add_f32_dpp v112, v112, v112 row_mirror row_mask:0xf bank_mask:0xf
	s_nop 1
	v_add_f32_dpp v112, v112, v112 row_bcast:15 row_mask:0xa bank_mask:0xf
	s_nop 1
	v_add_f32_dpp v112, v112, v112 row_bcast:31 row_mask:0xc bank_mask:0xf
	s_nop 1
	v_readlane_b32 s14, v112, 63
	s_nop 3
	s_mov_b32 s15, s14
	v_pk_fma_f32 v[48:49], s[14:15], v[116:117], v[48:49]
	v_pk_fma_f32 v[50:51], s[14:15], v[116:117], v[50:51]
	v_pk_fma_f32 v[52:53], s[14:15], v[116:117], v[52:53]
	v_pk_fma_f32 v[54:55], s[14:15], v[116:117], v[54:55]
	v_pk_fma_f32 v[56:57], s[14:15], v[116:117], v[56:57]
	v_pk_fma_f32 v[58:59], s[14:15], v[116:117], v[58:59]
	v_pk_fma_f32 v[60:61], s[14:15], v[116:117], v[60:61]
	v_pk_fma_f32 v[62:63], s[14:15], v[116:117], v[62:63]
	v_pk_mul_f32 v[96:97], v[48:49], v[48:49]
	v_pk_fma_f32 v[96:97], v[50:51], v[50:51], v[96:97]
	v_pk_fma_f32 v[96:97], v[52:53], v[52:53], v[96:97]
	v_pk_fma_f32 v[96:97], v[54:55], v[54:55], v[96:97]
	v_pk_fma_f32 v[96:97], v[56:57], v[56:57], v[96:97]
	v_pk_fma_f32 v[96:97], v[58:59], v[58:59], v[96:97]
	v_pk_fma_f32 v[96:97], v[60:61], v[60:61], v[96:97]
	v_pk_fma_f32 v[96:97], v[62:63], v[62:63], v[96:97]
	v_add_f32_e32 v114, v96, v97
	s_nop 1
	v_add_f32_dpp v112, v114, v114 quad_perm:[1,0,3,2] row_mask:0xf bank_mask:0xf
	s_nop 1
	v_add_f32_dpp v112, v112, v112 quad_perm:[2,3,0,1] row_mask:0xf bank_mask:0xf
	s_nop 1
	v_add_f32_dpp v112, v112, v112 row_half_mirror row_mask:0xf bank_mask:0xf
	s_nop 1
	v_add_f32_dpp v112, v112, v112 row_mirror row_mask:0xf bank_mask:0xf
	s_nop 1
	v_add_f32_dpp v112, v112, v112 row_bcast:15 row_mask:0xa bank_mask:0xf
	s_nop 1
	v_add_f32_dpp v112, v112, v112 row_bcast:31 row_mask:0xc bank_mask:0xf
	s_nop 1
	v_readlane_b32 s14, v112, 63
	s_nop 3
	v_fma_f32 v118, s14, v122, v123
	v_rsq_f32_e32 v118, v118
	s_nop 0
	v_pk_mul_f32 v[48:49], v[48:49], v[118:119] op_sel_hi:[1,0]
	v_pk_mul_f32 v[50:51], v[50:51], v[118:119] op_sel_hi:[1,0]
	v_pk_mul_f32 v[52:53], v[52:53], v[118:119] op_sel_hi:[1,0]
	v_pk_mul_f32 v[54:55], v[54:55], v[118:119] op_sel_hi:[1,0]
	v_pk_mul_f32 v[56:57], v[56:57], v[118:119] op_sel_hi:[1,0]
	v_pk_mul_f32 v[58:59], v[58:59], v[118:119] op_sel_hi:[1,0]
	v_pk_mul_f32 v[60:61], v[60:61], v[118:119] op_sel_hi:[1,0]
	v_pk_mul_f32 v[62:63], v[62:63], v[118:119] op_sel_hi:[1,0]
	v_pk_fma_f32 v[48:49], v[48:49], v[0:1], v[16:17]
	v_pk_fma_f32 v[50:51], v[50:51], v[2:3], v[18:19]
	v_pk_fma_f32 v[52:53], v[52:53], v[4:5], v[20:21]
	v_pk_fma_f32 v[54:55], v[54:55], v[6:7], v[22:23]
	v_pk_fma_f32 v[56:57], v[56:57], v[8:9], v[24:25]
	v_pk_fma_f32 v[58:59], v[58:59], v[10:11], v[26:27]
	v_pk_fma_f32 v[60:61], v[60:61], v[12:13], v[28:29]
	v_pk_fma_f32 v[62:63], v[62:63], v[14:15], v[30:31]
	v_cvt_pk_bf16_f32 v96, v48, v49
	v_cvt_pk_bf16_f32 v97, v50, v51
	v_cvt_pk_bf16_f32 v98, v52, v53
	v_cvt_pk_bf16_f32 v99, v54, v55
	v_cvt_pk_bf16_f32 v100, v56, v57
	v_cvt_pk_bf16_f32 v101, v58, v59
	v_cvt_pk_bf16_f32 v102, v60, v61
	v_cvt_pk_bf16_f32 v103, v62, v63
	global_store_dwordx2 v121, v[96:97], s[6:7] offset:0
	global_store_dwordx2 v121, v[98:99], s[6:7] offset:512
	global_store_dwordx2 v121, v[100:101], s[6:7] offset:1024
	global_store_dwordx2 v121, v[102:103], s[6:7] offset:1536
	s_add_u32 s6, s6, 0x800
	s_addc_u32 s7, s7, 0
	global_load_dwordx4 v[48:51], v120, s[4:5] offset:0
	global_load_dwordx4 v[52:55], v120, s[4:5] offset:1024
	global_load_dwordx4 v[56:59], v120, s[4:5] offset:2048
	global_load_dwordx4 v[60:63], v120, s[4:5] offset:3072
	s_add_u32 s4, s4, 0x1000
	s_addc_u32 s5, s5, 0
	s_waitcnt vmcnt(20)
	v_pk_add_f32 v[96:97], v[64:65], v[66:67]
	v_pk_add_f32 v[96:97], v[96:97], v[68:69]
	v_pk_add_f32 v[96:97], v[96:97], v[70:71]
	v_pk_add_f32 v[96:97], v[96:97], v[72:73]
	v_pk_add_f32 v[96:97], v[96:97], v[74:75]
	v_pk_add_f32 v[96:97], v[96:97], v[76:77]
	v_pk_add_f32 v[96:97], v[96:97], v[78:79]
	v_add_f32_e32 v114, v96, v97
	s_nop 1
	v_add_f32_dpp v112, v114, v114 quad_perm:[1,0,3,2] row_mask:0xf bank_mask:0xf
	s_nop 1
	v_add_f32_dpp v112, v112, v112 quad_perm:[2,3,0,1] row_mask:0xf bank_mask:0xf
	s_nop 1
	v_add_f32_dpp v112, v112, v112 row_half_mirror row_mask:0xf bank_mask:0xf
	s_nop 1
	v_add_f32_dpp v112, v112, v112 row_mirror row_mask:0xf bank_mask:0xf
	s_nop 1
	v_add_f32_dpp v112, v112, v112 row_bcast:15 row_mask:0xa bank_mask:0xf
	s_nop 1
	v_add_f32_dpp v112, v112, v112 row_bcast:31 row_mask:0xc bank_mask:0xf
	s_nop 1
	v_readlane_b32 s14, v112, 63
	s_nop 3
	s_mov_b32 s15, s14
	v_pk_fma_f32 v[64:65], s[14:15], v[116:117], v[64:65]
	v_pk_fma_f32 v[66:67], s[14:15], v[116:117], v[66:67]
	v_pk_fma_f32 v[68:69], s[14:15], v[116:117], v[68:69]
	v_pk_fma_f32 v[70:71], s[14:15], v[116:117], v[70:71]
	v_pk_fma_f32 v[72:73], s[14:15], v[116:117], v[72:73]
	v_pk_fma_f32 v[74:75], s[14:15], v[116:117], v[74:75]
	v_pk_fma_f32 v[76:77], s[14:15], v[116:117], v[76:77]
	v_pk_fma_f32 v[78:79], s[14:15], v[116:117], v[78:79]
	v_pk_mul_f32 v[96:97], v[64:65], v[64:65]
	v_pk_fma_f32 v[96:97], v[66:67], v[66:67], v[96:97]
	v_pk_fma_f32 v[96:97], v[68:69], v[68:69], v[96:97]
	v_pk_fma_f32 v[96:97], v[70:71], v[70:71], v[96:97]
	v_pk_fma_f32 v[96:97], v[72:73], v[72:73], v[96:97]
	v_pk_fma_f32 v[96:97], v[74:75], v[74:75], v[96:97]
	v_pk_fma_f32 v[96:97], v[76:77], v[76:77], v[96:97]
	v_pk_fma_f32 v[96:97], v[78:79], v[78:79], v[96:97]
	v_add_f32_e32 v114, v96, v97
	s_nop 1
	v_add_f32_dpp v112, v114, v114 quad_perm:[1,0,3,2] row_mask:0xf bank_mask:0xf
	s_nop 1
	v_add_f32_dpp v112, v112, v112 quad_perm:[2,3,0,1] row_mask:0xf bank_mask:0xf
	s_nop 1
	v_add_f32_dpp v112, v112, v112 row_half_mirror row_mask:0xf bank_mask:0xf
	s_nop 1
	v_add_f32_dpp v112, v112, v112 row_mirror row_mask:0xf bank_mask:0xf
	s_nop 1
	v_add_f32_dpp v112, v112, v112 row_bcast:15 row_mask:0xa bank_mask:0xf
	s_nop 1
	v_add_f32_dpp v112, v112, v112 row_bcast:31 row_mask:0xc bank_mask:0xf
	s_nop 1
	v_readlane_b32 s14, v112, 63
	s_nop 3
	v_fma_f32 v118, s14, v122, v123
	v_rsq_f32_e32 v118, v118
	s_nop 0
	v_pk_mul_f32 v[64:65], v[64:65], v[118:119] op_sel_hi:[1,0]
	v_pk_mul_f32 v[66:67], v[66:67], v[118:119] op_sel_hi:[1,0]
	v_pk_mul_f32 v[68:69], v[68:69], v[118:119] op_sel_hi:[1,0]
	v_pk_mul_f32 v[70:71], v[70:71], v[118:119] op_sel_hi:[1,0]
	v_pk_mul_f32 v[72:73], v[72:73], v[118:119] op_sel_hi:[1,0]
	v_pk_mul_f32 v[74:75], v[74:75], v[118:119] op_sel_hi:[1,0]
	v_pk_mul_f32 v[76:77], v[76:77], v[118:119] op_sel_hi:[1,0]
	v_pk_mul_f32 v[78:79], v[78:79], v[118:119] op_sel_hi:[1,0]
	v_pk_fma_f32 v[64:65], v[64:65], v[0:1], v[16:17]
	v_pk_fma_f32 v[66:67], v[66:67], v[2:3], v[18:19]
	v_pk_fma_f32 v[68:69], v[68:69], v[4:5], v[20:21]
	v_pk_fma_f32 v[70:71], v[70:71], v[6:7], v[22:23]
	v_pk_fma_f32 v[72:73], v[72:73], v[8:9], v[24:25]
	v_pk_fma_f32 v[74:75], v[74:75], v[10:11], v[26:27]
	v_pk_fma_f32 v[76:77], v[76:77], v[12:13], v[28:29]
	v_pk_fma_f32 v[78:79], v[78:79], v[14:15], v[30:31]
	v_cvt_pk_bf16_f32 v96, v64, v65
	v_cvt_pk_bf16_f32 v97, v66, v67
	v_cvt_pk_bf16_f32 v98, v68, v69
	v_cvt_pk_bf16_f32 v99, v70, v71
	v_cvt_pk_bf16_f32 v100, v72, v73
	v_cvt_pk_bf16_f32 v101, v74, v75
	v_cvt_pk_bf16_f32 v102, v76, v77
	v_cvt_pk_bf16_f32 v103, v78, v79
	global_store_dwordx2 v121, v[96:97], s[6:7] offset:0
	global_store_dwordx2 v121, v[98:99], s[6:7] offset:512
	global_store_dwordx2 v121, v[100:101], s[6:7] offset:1024
	global_store_dwordx2 v121, v[102:103], s[6:7] offset:1536
	s_add_u32 s6, s6, 0x800
	s_addc_u32 s7, s7, 0
	global_load_dwordx4 v[64:67], v120, s[4:5] offset:0
	global_load_dwordx4 v[68:71], v120, s[4:5] offset:1024
	global_load_dwordx4 v[72:75], v120, s[4:5] offset:2048
	global_load_dwordx4 v[76:79], v120, s[4:5] offset:3072
	s_add_u32 s4, s4, 0x1000
	s_addc_u32 s5, s5, 0
	s_waitcnt vmcnt(24)
	v_pk_add_f32 v[96:97], v[80:81], v[82:83]
	v_pk_add_f32 v[96:97], v[96:97], v[84:85]
	v_pk_add_f32 v[96:97], v[96:97], v[86:87]
	v_pk_add_f32 v[96:97], v[96:97], v[88:89]
	v_pk_add_f32 v[96:97], v[96:97], v[90:91]
	v_pk_add_f32 v[96:97], v[96:97], v[92:93]
	v_pk_add_f32 v[96:97], v[96:97], v[94:95]
	v_add_f32_e32 v114, v96, v97
	s_nop 1
	v_add_f32_dpp v112, v114, v114 quad_perm:[1,0,3,2] row_mask:0xf bank_mask:0xf
	s_nop 1
	v_add_f32_dpp v112, v112, v112 quad_perm:[2,3,0,1] row_mask:0xf bank_mask:0xf
	s_nop 1
	v_add_f32_dpp v112, v112, v112 row_half_mirror row_mask:0xf bank_mask:0xf
	s_nop 1
	v_add_f32_dpp v112, v112, v112 row_mirror row_mask:0xf bank_mask:0xf
	s_nop 1
	v_add_f32_dpp v112, v112, v112 row_bcast:15 row_mask:0xa bank_mask:0xf
	s_nop 1
	v_add_f32_dpp v112, v112, v112 row_bcast:31 row_mask:0xc bank_mask:0xf
	s_nop 1
	v_readlane_b32 s14, v112, 63
	s_nop 3
	s_mov_b32 s15, s14
	v_pk_fma_f32 v[80:81], s[14:15], v[116:117], v[80:81]
	v_pk_fma_f32 v[82:83], s[14:15], v[116:117], v[82:83]
	v_pk_fma_f32 v[84:85], s[14:15], v[116:117], v[84:85]
	v_pk_fma_f32 v[86:87], s[14:15], v[116:117], v[86:87]
	v_pk_fma_f32 v[88:89], s[14:15], v[116:117], v[88:89]
	v_pk_fma_f32 v[90:91], s[14:15], v[116:117], v[90:91]
	v_pk_fma_f32 v[92:93], s[14:15], v[116:117], v[92:93]
	v_pk_fma_f32 v[94:95], s[14:15], v[116:117], v[94:95]
	v_pk_mul_f32 v[96:97], v[80:81], v[80:81]
	v_pk_fma_f32 v[96:97], v[82:83], v[82:83], v[96:97]
	v_pk_fma_f32 v[96:97], v[84:85], v[84:85], v[96:97]
	v_pk_fma_f32 v[96:97], v[86:87], v[86:87], v[96:97]
	v_pk_fma_f32 v[96:97], v[88:89], v[88:89], v[96:97]
	v_pk_fma_f32 v[96:97], v[90:91], v[90:91], v[96:97]
	v_pk_fma_f32 v[96:97], v[92:93], v[92:93], v[96:97]
	v_pk_fma_f32 v[96:97], v[94:95], v[94:95], v[96:97]
	v_add_f32_e32 v114, v96, v97
	s_nop 1
	v_add_f32_dpp v112, v114, v114 quad_perm:[1,0,3,2] row_mask:0xf bank_mask:0xf
	s_nop 1
	v_add_f32_dpp v112, v112, v112 quad_perm:[2,3,0,1] row_mask:0xf bank_mask:0xf
	s_nop 1
	v_add_f32_dpp v112, v112, v112 row_half_mirror row_mask:0xf bank_mask:0xf
	s_nop 1
	v_add_f32_dpp v112, v112, v112 row_mirror row_mask:0xf bank_mask:0xf
	s_nop 1
	v_add_f32_dpp v112, v112, v112 row_bcast:15 row_mask:0xa bank_mask:0xf
	s_nop 1
	v_add_f32_dpp v112, v112, v112 row_bcast:31 row_mask:0xc bank_mask:0xf
	s_nop 1
	v_readlane_b32 s14, v112, 63
	s_nop 3
	v_fma_f32 v118, s14, v122, v123
	v_rsq_f32_e32 v118, v118
	s_nop 0
	v_pk_mul_f32 v[80:81], v[80:81], v[118:119] op_sel_hi:[1,0]
	v_pk_mul_f32 v[82:83], v[82:83], v[118:119] op_sel_hi:[1,0]
	v_pk_mul_f32 v[84:85], v[84:85], v[118:119] op_sel_hi:[1,0]
	v_pk_mul_f32 v[86:87], v[86:87], v[118:119] op_sel_hi:[1,0]
	v_pk_mul_f32 v[88:89], v[88:89], v[118:119] op_sel_hi:[1,0]
	v_pk_mul_f32 v[90:91], v[90:91], v[118:119] op_sel_hi:[1,0]
	v_pk_mul_f32 v[92:93], v[92:93], v[118:119] op_sel_hi:[1,0]
	v_pk_mul_f32 v[94:95], v[94:95], v[118:119] op_sel_hi:[1,0]
	v_pk_fma_f32 v[80:81], v[80:81], v[0:1], v[16:17]
	v_pk_fma_f32 v[82:83], v[82:83], v[2:3], v[18:19]
	v_pk_fma_f32 v[84:85], v[84:85], v[4:5], v[20:21]
	v_pk_fma_f32 v[86:87], v[86:87], v[6:7], v[22:23]
	v_pk_fma_f32 v[88:89], v[88:89], v[8:9], v[24:25]
	v_pk_fma_f32 v[90:91], v[90:91], v[10:11], v[26:27]
	v_pk_fma_f32 v[92:93], v[92:93], v[12:13], v[28:29]
	v_pk_fma_f32 v[94:95], v[94:95], v[14:15], v[30:31]
	v_cvt_pk_bf16_f32 v96, v80, v81
	v_cvt_pk_bf16_f32 v97, v82, v83
	v_cvt_pk_bf16_f32 v98, v84, v85
	v_cvt_pk_bf16_f32 v99, v86, v87
	v_cvt_pk_bf16_f32 v100, v88, v89
	v_cvt_pk_bf16_f32 v101, v90, v91
	v_cvt_pk_bf16_f32 v102, v92, v93
	v_cvt_pk_bf16_f32 v103, v94, v95
	global_store_dwordx2 v121, v[96:97], s[6:7] offset:0
	global_store_dwordx2 v121, v[98:99], s[6:7] offset:512
	global_store_dwordx2 v121, v[100:101], s[6:7] offset:1024
	global_store_dwordx2 v121, v[102:103], s[6:7] offset:1536
	s_add_u32 s6, s6, 0x800
	s_addc_u32 s7, s7, 0
	global_load_dwordx4 v[80:83], v120, s[4:5] offset:0
	global_load_dwordx4 v[84:87], v120, s[4:5] offset:1024
	global_load_dwordx4 v[88:91], v120, s[4:5] offset:2048
	global_load_dwordx4 v[92:95], v120, s[4:5] offset:3072
	s_add_u32 s4, s4, 0x1000
	s_addc_u32 s5, s5, 0
	s_waitcnt vmcnt(24)
	v_pk_add_f32 v[96:97], v[32:33], v[34:35]
	v_pk_add_f32 v[96:97], v[96:97], v[36:37]
	v_pk_add_f32 v[96:97], v[96:97], v[38:39]
	v_pk_add_f32 v[96:97], v[96:97], v[40:41]
	v_pk_add_f32 v[96:97], v[96:97], v[42:43]
	v_pk_add_f32 v[96:97], v[96:97], v[44:45]
	v_pk_add_f32 v[96:97], v[96:97], v[46:47]
	v_add_f32_e32 v114, v96, v97
	s_nop 1
	v_add_f32_dpp v112, v114, v114 quad_perm:[1,0,3,2] row_mask:0xf bank_mask:0xf
	s_nop 1
	v_add_f32_dpp v112, v112, v112 quad_perm:[2,3,0,1] row_mask:0xf bank_mask:0xf
	s_nop 1
	v_add_f32_dpp v112, v112, v112 row_half_mirror row_mask:0xf bank_mask:0xf
	s_nop 1
	v_add_f32_dpp v112, v112, v112 row_mirror row_mask:0xf bank_mask:0xf
	s_nop 1
	v_add_f32_dpp v112, v112, v112 row_bcast:15 row_mask:0xa bank_mask:0xf
	s_nop 1
	v_add_f32_dpp v112, v112, v112 row_bcast:31 row_mask:0xc bank_mask:0xf
	s_nop 1
	v_readlane_b32 s14, v112, 63
	s_nop 3
	s_mov_b32 s15, s14
	v_pk_fma_f32 v[32:33], s[14:15], v[116:117], v[32:33]
	v_pk_fma_f32 v[34:35], s[14:15], v[116:117], v[34:35]
	v_pk_fma_f32 v[36:37], s[14:15], v[116:117], v[36:37]
	v_pk_fma_f32 v[38:39], s[14:15], v[116:117], v[38:39]
	v_pk_fma_f32 v[40:41], s[14:15], v[116:117], v[40:41]
	v_pk_fma_f32 v[42:43], s[14:15], v[116:117], v[42:43]
	v_pk_fma_f32 v[44:45], s[14:15], v[116:117], v[44:45]
	v_pk_fma_f32 v[46:47], s[14:15], v[116:117], v[46:47]
	v_pk_mul_f32 v[96:97], v[32:33], v[32:33]
	v_pk_fma_f32 v[96:97], v[34:35], v[34:35], v[96:97]
	v_pk_fma_f32 v[96:97], v[36:37], v[36:37], v[96:97]
	v_pk_fma_f32 v[96:97], v[38:39], v[38:39], v[96:97]
	v_pk_fma_f32 v[96:97], v[40:41], v[40:41], v[96:97]
	v_pk_fma_f32 v[96:97], v[42:43], v[42:43], v[96:97]
	v_pk_fma_f32 v[96:97], v[44:45], v[44:45], v[96:97]
	v_pk_fma_f32 v[96:97], v[46:47], v[46:47], v[96:97]
	v_add_f32_e32 v114, v96, v97
	s_nop 1
	v_add_f32_dpp v112, v114, v114 quad_perm:[1,0,3,2] row_mask:0xf bank_mask:0xf
	s_nop 1
	v_add_f32_dpp v112, v112, v112 quad_perm:[2,3,0,1] row_mask:0xf bank_mask:0xf
	s_nop 1
	v_add_f32_dpp v112, v112, v112 row_half_mirror row_mask:0xf bank_mask:0xf
	s_nop 1
	v_add_f32_dpp v112, v112, v112 row_mirror row_mask:0xf bank_mask:0xf
	s_nop 1
	v_add_f32_dpp v112, v112, v112 row_bcast:15 row_mask:0xa bank_mask:0xf
	s_nop 1
	v_add_f32_dpp v112, v112, v112 row_bcast:31 row_mask:0xc bank_mask:0xf
	s_nop 1
	v_readlane_b32 s14, v112, 63
	s_nop 3
	v_fma_f32 v118, s14, v122, v123
	v_rsq_f32_e32 v118, v118
	s_nop 0
	v_pk_mul_f32 v[32:33], v[32:33], v[118:119] op_sel_hi:[1,0]
	v_pk_mul_f32 v[34:35], v[34:35], v[118:119] op_sel_hi:[1,0]
	v_pk_mul_f32 v[36:37], v[36:37], v[118:119] op_sel_hi:[1,0]
	v_pk_mul_f32 v[38:39], v[38:39], v[118:119] op_sel_hi:[1,0]
	v_pk_mul_f32 v[40:41], v[40:41], v[118:119] op_sel_hi:[1,0]
	v_pk_mul_f32 v[42:43], v[42:43], v[118:119] op_sel_hi:[1,0]
	v_pk_mul_f32 v[44:45], v[44:45], v[118:119] op_sel_hi:[1,0]
	v_pk_mul_f32 v[46:47], v[46:47], v[118:119] op_sel_hi:[1,0]
	v_pk_fma_f32 v[32:33], v[32:33], v[0:1], v[16:17]
	v_pk_fma_f32 v[34:35], v[34:35], v[2:3], v[18:19]
	v_pk_fma_f32 v[36:37], v[36:37], v[4:5], v[20:21]
	v_pk_fma_f32 v[38:39], v[38:39], v[6:7], v[22:23]
	v_pk_fma_f32 v[40:41], v[40:41], v[8:9], v[24:25]
	v_pk_fma_f32 v[42:43], v[42:43], v[10:11], v[26:27]
	v_pk_fma_f32 v[44:45], v[44:45], v[12:13], v[28:29]
	v_pk_fma_f32 v[46:47], v[46:47], v[14:15], v[30:31]
	v_cvt_pk_bf16_f32 v96, v32, v33
	v_cvt_pk_bf16_f32 v97, v34, v35
	v_cvt_pk_bf16_f32 v98, v36, v37
	v_cvt_pk_bf16_f32 v99, v38, v39
	v_cvt_pk_bf16_f32 v100, v40, v41
	v_cvt_pk_bf16_f32 v101, v42, v43
	v_cvt_pk_bf16_f32 v102, v44, v45
	v_cvt_pk_bf16_f32 v103, v46, v47
	global_store_dwordx2 v121, v[96:97], s[6:7] offset:0
	global_store_dwordx2 v121, v[98:99], s[6:7] offset:512
	global_store_dwordx2 v121, v[100:101], s[6:7] offset:1024
	global_store_dwordx2 v121, v[102:103], s[6:7] offset:1536
	s_add_u32 s6, s6, 0x800
	s_addc_u32 s7, s7, 0
	global_load_dwordx4 v[32:35], v120, s[4:5] offset:0
	global_load_dwordx4 v[36:39], v120, s[4:5] offset:1024
	global_load_dwordx4 v[40:43], v120, s[4:5] offset:2048
	global_load_dwordx4 v[44:47], v120, s[4:5] offset:3072
	s_add_u32 s4, s4, 0x1000
	s_addc_u32 s5, s5, 0
	s_waitcnt vmcnt(24)
	v_pk_add_f32 v[96:97], v[48:49], v[50:51]
	v_pk_add_f32 v[96:97], v[96:97], v[52:53]
	v_pk_add_f32 v[96:97], v[96:97], v[54:55]
	v_pk_add_f32 v[96:97], v[96:97], v[56:57]
	v_pk_add_f32 v[96:97], v[96:97], v[58:59]
	v_pk_add_f32 v[96:97], v[96:97], v[60:61]
	v_pk_add_f32 v[96:97], v[96:97], v[62:63]
	v_add_f32_e32 v114, v96, v97
	s_nop 1
	v_add_f32_dpp v112, v114, v114 quad_perm:[1,0,3,2] row_mask:0xf bank_mask:0xf
	s_nop 1
	v_add_f32_dpp v112, v112, v112 quad_perm:[2,3,0,1] row_mask:0xf bank_mask:0xf
	s_nop 1
	v_add_f32_dpp v112, v112, v112 row_half_mirror row_mask:0xf bank_mask:0xf
	s_nop 1
	v_add_f32_dpp v112, v112, v112 row_mirror row_mask:0xf bank_mask:0xf
	s_nop 1
	v_add_f32_dpp v112, v112, v112 row_bcast:15 row_mask:0xa bank_mask:0xf
	s_nop 1
	v_add_f32_dpp v112, v112, v112 row_bcast:31 row_mask:0xc bank_mask:0xf
	s_nop 1
	v_readlane_b32 s14, v112, 63
	s_nop 3
	s_mov_b32 s15, s14
	v_pk_fma_f32 v[48:49], s[14:15], v[116:117], v[48:49]
	v_pk_fma_f32 v[50:51], s[14:15], v[116:117], v[50:51]
	v_pk_fma_f32 v[52:53], s[14:15], v[116:117], v[52:53]
	v_pk_fma_f32 v[54:55], s[14:15], v[116:117], v[54:55]
	v_pk_fma_f32 v[56:57], s[14:15], v[116:117], v[56:57]
	v_pk_fma_f32 v[58:59], s[14:15], v[116:117], v[58:59]
	v_pk_fma_f32 v[60:61], s[14:15], v[116:117], v[60:61]
	v_pk_fma_f32 v[62:63], s[14:15], v[116:117], v[62:63]
	v_pk_mul_f32 v[96:97], v[48:49], v[48:49]
	v_pk_fma_f32 v[96:97], v[50:51], v[50:51], v[96:97]
	v_pk_fma_f32 v[96:97], v[52:53], v[52:53], v[96:97]
	v_pk_fma_f32 v[96:97], v[54:55], v[54:55], v[96:97]
	v_pk_fma_f32 v[96:97], v[56:57], v[56:57], v[96:97]
	v_pk_fma_f32 v[96:97], v[58:59], v[58:59], v[96:97]
	v_pk_fma_f32 v[96:97], v[60:61], v[60:61], v[96:97]
	v_pk_fma_f32 v[96:97], v[62:63], v[62:63], v[96:97]
	v_add_f32_e32 v114, v96, v97
	s_nop 1
	v_add_f32_dpp v112, v114, v114 quad_perm:[1,0,3,2] row_mask:0xf bank_mask:0xf
	s_nop 1
	v_add_f32_dpp v112, v112, v112 quad_perm:[2,3,0,1] row_mask:0xf bank_mask:0xf
	s_nop 1
	v_add_f32_dpp v112, v112, v112 row_half_mirror row_mask:0xf bank_mask:0xf
	s_nop 1
	v_add_f32_dpp v112, v112, v112 row_mirror row_mask:0xf bank_mask:0xf
	s_nop 1
	v_add_f32_dpp v112, v112, v112 row_bcast:15 row_mask:0xa bank_mask:0xf
	s_nop 1
	v_add_f32_dpp v112, v112, v112 row_bcast:31 row_mask:0xc bank_mask:0xf
	s_nop 1
	v_readlane_b32 s14, v112, 63
	s_nop 3
	v_fma_f32 v118, s14, v122, v123
	v_rsq_f32_e32 v118, v118
	s_nop 0
	v_pk_mul_f32 v[48:49], v[48:49], v[118:119] op_sel_hi:[1,0]
	v_pk_mul_f32 v[50:51], v[50:51], v[118:119] op_sel_hi:[1,0]
	v_pk_mul_f32 v[52:53], v[52:53], v[118:119] op_sel_hi:[1,0]
	v_pk_mul_f32 v[54:55], v[54:55], v[118:119] op_sel_hi:[1,0]
	v_pk_mul_f32 v[56:57], v[56:57], v[118:119] op_sel_hi:[1,0]
	v_pk_mul_f32 v[58:59], v[58:59], v[118:119] op_sel_hi:[1,0]
	v_pk_mul_f32 v[60:61], v[60:61], v[118:119] op_sel_hi:[1,0]
	v_pk_mul_f32 v[62:63], v[62:63], v[118:119] op_sel_hi:[1,0]
	v_pk_fma_f32 v[48:49], v[48:49], v[0:1], v[16:17]
	v_pk_fma_f32 v[50:51], v[50:51], v[2:3], v[18:19]
	v_pk_fma_f32 v[52:53], v[52:53], v[4:5], v[20:21]
	v_pk_fma_f32 v[54:55], v[54:55], v[6:7], v[22:23]
	v_pk_fma_f32 v[56:57], v[56:57], v[8:9], v[24:25]
	v_pk_fma_f32 v[58:59], v[58:59], v[10:11], v[26:27]
	v_pk_fma_f32 v[60:61], v[60:61], v[12:13], v[28:29]
	v_pk_fma_f32 v[62:63], v[62:63], v[14:15], v[30:31]
	v_cvt_pk_bf16_f32 v96, v48, v49
	v_cvt_pk_bf16_f32 v97, v50, v51
	v_cvt_pk_bf16_f32 v98, v52, v53
	v_cvt_pk_bf16_f32 v99, v54, v55
	v_cvt_pk_bf16_f32 v100, v56, v57
	v_cvt_pk_bf16_f32 v101, v58, v59
	v_cvt_pk_bf16_f32 v102, v60, v61
	v_cvt_pk_bf16_f32 v103, v62, v63
	global_store_dwordx2 v121, v[96:97], s[6:7] offset:0
	global_store_dwordx2 v121, v[98:99], s[6:7] offset:512
	global_store_dwordx2 v121, v[100:101], s[6:7] offset:1024
	global_store_dwordx2 v121, v[102:103], s[6:7] offset:1536
	s_add_u32 s6, s6, 0x800
	s_addc_u32 s7, s7, 0
	global_load_dwordx4 v[48:51], v120, s[4:5] offset:0
	global_load_dwordx4 v[52:55], v120, s[4:5] offset:1024
	global_load_dwordx4 v[56:59], v120, s[4:5] offset:2048
	global_load_dwordx4 v[60:63], v120, s[4:5] offset:3072
	s_add_u32 s4, s4, 0x1000
	s_addc_u32 s5, s5, 0
	s_waitcnt vmcnt(24)
	v_pk_add_f32 v[96:97], v[64:65], v[66:67]
	v_pk_add_f32 v[96:97], v[96:97], v[68:69]
	v_pk_add_f32 v[96:97], v[96:97], v[70:71]
	v_pk_add_f32 v[96:97], v[96:97], v[72:73]
	v_pk_add_f32 v[96:97], v[96:97], v[74:75]
	v_pk_add_f32 v[96:97], v[96:97], v[76:77]
	v_pk_add_f32 v[96:97], v[96:97], v[78:79]
	v_add_f32_e32 v114, v96, v97
	s_nop 1
	v_add_f32_dpp v112, v114, v114 quad_perm:[1,0,3,2] row_mask:0xf bank_mask:0xf
	s_nop 1
	v_add_f32_dpp v112, v112, v112 quad_perm:[2,3,0,1] row_mask:0xf bank_mask:0xf
	s_nop 1
	v_add_f32_dpp v112, v112, v112 row_half_mirror row_mask:0xf bank_mask:0xf
	s_nop 1
	v_add_f32_dpp v112, v112, v112 row_mirror row_mask:0xf bank_mask:0xf
	s_nop 1
	v_add_f32_dpp v112, v112, v112 row_bcast:15 row_mask:0xa bank_mask:0xf
	s_nop 1
	v_add_f32_dpp v112, v112, v112 row_bcast:31 row_mask:0xc bank_mask:0xf
	s_nop 1
	v_readlane_b32 s14, v112, 63
	s_nop 3
	s_mov_b32 s15, s14
	v_pk_fma_f32 v[64:65], s[14:15], v[116:117], v[64:65]
	v_pk_fma_f32 v[66:67], s[14:15], v[116:117], v[66:67]
	v_pk_fma_f32 v[68:69], s[14:15], v[116:117], v[68:69]
	v_pk_fma_f32 v[70:71], s[14:15], v[116:117], v[70:71]
	v_pk_fma_f32 v[72:73], s[14:15], v[116:117], v[72:73]
	v_pk_fma_f32 v[74:75], s[14:15], v[116:117], v[74:75]
	v_pk_fma_f32 v[76:77], s[14:15], v[116:117], v[76:77]
	v_pk_fma_f32 v[78:79], s[14:15], v[116:117], v[78:79]
	v_pk_mul_f32 v[96:97], v[64:65], v[64:65]
	v_pk_fma_f32 v[96:97], v[66:67], v[66:67], v[96:97]
	v_pk_fma_f32 v[96:97], v[68:69], v[68:69], v[96:97]
	v_pk_fma_f32 v[96:97], v[70:71], v[70:71], v[96:97]
	v_pk_fma_f32 v[96:97], v[72:73], v[72:73], v[96:97]
	v_pk_fma_f32 v[96:97], v[74:75], v[74:75], v[96:97]
	v_pk_fma_f32 v[96:97], v[76:77], v[76:77], v[96:97]
	v_pk_fma_f32 v[96:97], v[78:79], v[78:79], v[96:97]
	v_add_f32_e32 v114, v96, v97
	s_nop 1
	v_add_f32_dpp v112, v114, v114 quad_perm:[1,0,3,2] row_mask:0xf bank_mask:0xf
	s_nop 1
	v_add_f32_dpp v112, v112, v112 quad_perm:[2,3,0,1] row_mask:0xf bank_mask:0xf
	s_nop 1
	v_add_f32_dpp v112, v112, v112 row_half_mirror row_mask:0xf bank_mask:0xf
	s_nop 1
	v_add_f32_dpp v112, v112, v112 row_mirror row_mask:0xf bank_mask:0xf
	s_nop 1
	v_add_f32_dpp v112, v112, v112 row_bcast:15 row_mask:0xa bank_mask:0xf
	s_nop 1
	v_add_f32_dpp v112, v112, v112 row_bcast:31 row_mask:0xc bank_mask:0xf
	s_nop 1
	v_readlane_b32 s14, v112, 63
	s_nop 3
	v_fma_f32 v118, s14, v122, v123
	v_rsq_f32_e32 v118, v118
	s_nop 0
	v_pk_mul_f32 v[64:65], v[64:65], v[118:119] op_sel_hi:[1,0]
	v_pk_mul_f32 v[66:67], v[66:67], v[118:119] op_sel_hi:[1,0]
	v_pk_mul_f32 v[68:69], v[68:69], v[118:119] op_sel_hi:[1,0]
	v_pk_mul_f32 v[70:71], v[70:71], v[118:119] op_sel_hi:[1,0]
	v_pk_mul_f32 v[72:73], v[72:73], v[118:119] op_sel_hi:[1,0]
	v_pk_mul_f32 v[74:75], v[74:75], v[118:119] op_sel_hi:[1,0]
	v_pk_mul_f32 v[76:77], v[76:77], v[118:119] op_sel_hi:[1,0]
	v_pk_mul_f32 v[78:79], v[78:79], v[118:119] op_sel_hi:[1,0]
	v_pk_fma_f32 v[64:65], v[64:65], v[0:1], v[16:17]
	v_pk_fma_f32 v[66:67], v[66:67], v[2:3], v[18:19]
	v_pk_fma_f32 v[68:69], v[68:69], v[4:5], v[20:21]
	v_pk_fma_f32 v[70:71], v[70:71], v[6:7], v[22:23]
	v_pk_fma_f32 v[72:73], v[72:73], v[8:9], v[24:25]
	v_pk_fma_f32 v[74:75], v[74:75], v[10:11], v[26:27]
	v_pk_fma_f32 v[76:77], v[76:77], v[12:13], v[28:29]
	v_pk_fma_f32 v[78:79], v[78:79], v[14:15], v[30:31]
	v_cvt_pk_bf16_f32 v96, v64, v65
	v_cvt_pk_bf16_f32 v97, v66, v67
	v_cvt_pk_bf16_f32 v98, v68, v69
	v_cvt_pk_bf16_f32 v99, v70, v71
	v_cvt_pk_bf16_f32 v100, v72, v73
	v_cvt_pk_bf16_f32 v101, v74, v75
	v_cvt_pk_bf16_f32 v102, v76, v77
	v_cvt_pk_bf16_f32 v103, v78, v79
	global_store_dwordx2 v121, v[96:97], s[6:7] offset:0
	global_store_dwordx2 v121, v[98:99], s[6:7] offset:512
	global_store_dwordx2 v121, v[100:101], s[6:7] offset:1024
	global_store_dwordx2 v121, v[102:103], s[6:7] offset:1536
	s_add_u32 s6, s6, 0x800
	s_addc_u32 s7, s7, 0
	global_load_dwordx4 v[64:67], v120, s[4:5] offset:0
	global_load_dwordx4 v[68:71], v120, s[4:5] offset:1024
	global_load_dwordx4 v[72:75], v120, s[4:5] offset:2048
	global_load_dwordx4 v[76:79], v120, s[4:5] offset:3072
	s_add_u32 s4, s4, 0x1000
	s_addc_u32 s5, s5, 0
	s_waitcnt vmcnt(24)
	v_pk_add_f32 v[96:97], v[80:81], v[82:83]
	v_pk_add_f32 v[96:97], v[96:97], v[84:85]
	v_pk_add_f32 v[96:97], v[96:97], v[86:87]
	v_pk_add_f32 v[96:97], v[96:97], v[88:89]
	v_pk_add_f32 v[96:97], v[96:97], v[90:91]
	v_pk_add_f32 v[96:97], v[96:97], v[92:93]
	v_pk_add_f32 v[96:97], v[96:97], v[94:95]
	v_add_f32_e32 v114, v96, v97
	s_nop 1
	v_add_f32_dpp v112, v114, v114 quad_perm:[1,0,3,2] row_mask:0xf bank_mask:0xf
	s_nop 1
	v_add_f32_dpp v112, v112, v112 quad_perm:[2,3,0,1] row_mask:0xf bank_mask:0xf
	s_nop 1
	v_add_f32_dpp v112, v112, v112 row_half_mirror row_mask:0xf bank_mask:0xf
	s_nop 1
	v_add_f32_dpp v112, v112, v112 row_mirror row_mask:0xf bank_mask:0xf
	s_nop 1
	v_add_f32_dpp v112, v112, v112 row_bcast:15 row_mask:0xa bank_mask:0xf
	s_nop 1
	v_add_f32_dpp v112, v112, v112 row_bcast:31 row_mask:0xc bank_mask:0xf
	s_nop 1
	v_readlane_b32 s14, v112, 63
	s_nop 3
	s_mov_b32 s15, s14
	v_pk_fma_f32 v[80:81], s[14:15], v[116:117], v[80:81]
	v_pk_fma_f32 v[82:83], s[14:15], v[116:117], v[82:83]
	v_pk_fma_f32 v[84:85], s[14:15], v[116:117], v[84:85]
	v_pk_fma_f32 v[86:87], s[14:15], v[116:117], v[86:87]
	v_pk_fma_f32 v[88:89], s[14:15], v[116:117], v[88:89]
	v_pk_fma_f32 v[90:91], s[14:15], v[116:117], v[90:91]
	v_pk_fma_f32 v[92:93], s[14:15], v[116:117], v[92:93]
	v_pk_fma_f32 v[94:95], s[14:15], v[116:117], v[94:95]
	v_pk_mul_f32 v[96:97], v[80:81], v[80:81]
	v_pk_fma_f32 v[96:97], v[82:83], v[82:83], v[96:97]
	v_pk_fma_f32 v[96:97], v[84:85], v[84:85], v[96:97]
	v_pk_fma_f32 v[96:97], v[86:87], v[86:87], v[96:97]
	v_pk_fma_f32 v[96:97], v[88:89], v[88:89], v[96:97]
	v_pk_fma_f32 v[96:97], v[90:91], v[90:91], v[96:97]
	v_pk_fma_f32 v[96:97], v[92:93], v[92:93], v[96:97]
	v_pk_fma_f32 v[96:97], v[94:95], v[94:95], v[96:97]
	v_add_f32_e32 v114, v96, v97
	s_nop 1
	v_add_f32_dpp v112, v114, v114 quad_perm:[1,0,3,2] row_mask:0xf bank_mask:0xf
	s_nop 1
	v_add_f32_dpp v112, v112, v112 quad_perm:[2,3,0,1] row_mask:0xf bank_mask:0xf
	s_nop 1
	v_add_f32_dpp v112, v112, v112 row_half_mirror row_mask:0xf bank_mask:0xf
	s_nop 1
	v_add_f32_dpp v112, v112, v112 row_mirror row_mask:0xf bank_mask:0xf
	s_nop 1
	v_add_f32_dpp v112, v112, v112 row_bcast:15 row_mask:0xa bank_mask:0xf
	s_nop 1
	v_add_f32_dpp v112, v112, v112 row_bcast:31 row_mask:0xc bank_mask:0xf
	s_nop 1
	v_readlane_b32 s14, v112, 63
	s_nop 3
	v_fma_f32 v118, s14, v122, v123
	v_rsq_f32_e32 v118, v118
	s_nop 0
	v_pk_mul_f32 v[80:81], v[80:81], v[118:119] op_sel_hi:[1,0]
	v_pk_mul_f32 v[82:83], v[82:83], v[118:119] op_sel_hi:[1,0]
	v_pk_mul_f32 v[84:85], v[84:85], v[118:119] op_sel_hi:[1,0]
	v_pk_mul_f32 v[86:87], v[86:87], v[118:119] op_sel_hi:[1,0]
	v_pk_mul_f32 v[88:89], v[88:89], v[118:119] op_sel_hi:[1,0]
	v_pk_mul_f32 v[90:91], v[90:91], v[118:119] op_sel_hi:[1,0]
	v_pk_mul_f32 v[92:93], v[92:93], v[118:119] op_sel_hi:[1,0]
	v_pk_mul_f32 v[94:95], v[94:95], v[118:119] op_sel_hi:[1,0]
	v_pk_fma_f32 v[80:81], v[80:81], v[0:1], v[16:17]
	v_pk_fma_f32 v[82:83], v[82:83], v[2:3], v[18:19]
	v_pk_fma_f32 v[84:85], v[84:85], v[4:5], v[20:21]
	v_pk_fma_f32 v[86:87], v[86:87], v[6:7], v[22:23]
	v_pk_fma_f32 v[88:89], v[88:89], v[8:9], v[24:25]
	v_pk_fma_f32 v[90:91], v[90:91], v[10:11], v[26:27]
	v_pk_fma_f32 v[92:93], v[92:93], v[12:13], v[28:29]
	v_pk_fma_f32 v[94:95], v[94:95], v[14:15], v[30:31]
	v_cvt_pk_bf16_f32 v96, v80, v81
	v_cvt_pk_bf16_f32 v97, v82, v83
	v_cvt_pk_bf16_f32 v98, v84, v85
	v_cvt_pk_bf16_f32 v99, v86, v87
	v_cvt_pk_bf16_f32 v100, v88, v89
	v_cvt_pk_bf16_f32 v101, v90, v91
	v_cvt_pk_bf16_f32 v102, v92, v93
	v_cvt_pk_bf16_f32 v103, v94, v95
	global_store_dwordx2 v121, v[96:97], s[6:7] offset:0
	global_store_dwordx2 v121, v[98:99], s[6:7] offset:512
	global_store_dwordx2 v121, v[100:101], s[6:7] offset:1024
	global_store_dwordx2 v121, v[102:103], s[6:7] offset:1536
	s_add_u32 s6, s6, 0x800
	s_addc_u32 s7, s7, 0
	global_load_dwordx4 v[80:83], v120, s[4:5] offset:0
	global_load_dwordx4 v[84:87], v120, s[4:5] offset:1024
	global_load_dwordx4 v[88:91], v120, s[4:5] offset:2048
	global_load_dwordx4 v[92:95], v120, s[4:5] offset:3072
	s_add_u32 s4, s4, 0x1000
	s_addc_u32 s5, s5, 0
	s_waitcnt vmcnt(24)
	v_pk_add_f32 v[96:97], v[32:33], v[34:35]
	v_pk_add_f32 v[96:97], v[96:97], v[36:37]
	v_pk_add_f32 v[96:97], v[96:97], v[38:39]
	v_pk_add_f32 v[96:97], v[96:97], v[40:41]
	v_pk_add_f32 v[96:97], v[96:97], v[42:43]
	v_pk_add_f32 v[96:97], v[96:97], v[44:45]
	v_pk_add_f32 v[96:97], v[96:97], v[46:47]
	v_add_f32_e32 v114, v96, v97
	s_nop 1
	v_add_f32_dpp v112, v114, v114 quad_perm:[1,0,3,2] row_mask:0xf bank_mask:0xf
	s_nop 1
	v_add_f32_dpp v112, v112, v112 quad_perm:[2,3,0,1] row_mask:0xf bank_mask:0xf
	s_nop 1
	v_add_f32_dpp v112, v112, v112 row_half_mirror row_mask:0xf bank_mask:0xf
	s_nop 1
	v_add_f32_dpp v112, v112, v112 row_mirror row_mask:0xf bank_mask:0xf
	s_nop 1
	v_add_f32_dpp v112, v112, v112 row_bcast:15 row_mask:0xa bank_mask:0xf
	s_nop 1
	v_add_f32_dpp v112, v112, v112 row_bcast:31 row_mask:0xc bank_mask:0xf
	s_nop 1
	v_readlane_b32 s14, v112, 63
	s_nop 3
	s_mov_b32 s15, s14
	v_pk_fma_f32 v[32:33], s[14:15], v[116:117], v[32:33]
	v_pk_fma_f32 v[34:35], s[14:15], v[116:117], v[34:35]
	v_pk_fma_f32 v[36:37], s[14:15], v[116:117], v[36:37]
	v_pk_fma_f32 v[38:39], s[14:15], v[116:117], v[38:39]
	v_pk_fma_f32 v[40:41], s[14:15], v[116:117], v[40:41]
	v_pk_fma_f32 v[42:43], s[14:15], v[116:117], v[42:43]
	v_pk_fma_f32 v[44:45], s[14:15], v[116:117], v[44:45]
	v_pk_fma_f32 v[46:47], s[14:15], v[116:117], v[46:47]
	v_pk_mul_f32 v[96:97], v[32:33], v[32:33]
	v_pk_fma_f32 v[96:97], v[34:35], v[34:35], v[96:97]
	v_pk_fma_f32 v[96:97], v[36:37], v[36:37], v[96:97]
	v_pk_fma_f32 v[96:97], v[38:39], v[38:39], v[96:97]
	v_pk_fma_f32 v[96:97], v[40:41], v[40:41], v[96:97]
	v_pk_fma_f32 v[96:97], v[42:43], v[42:43], v[96:97]
	v_pk_fma_f32 v[96:97], v[44:45], v[44:45], v[96:97]
	v_pk_fma_f32 v[96:97], v[46:47], v[46:47], v[96:97]
	v_add_f32_e32 v114, v96, v97
	s_nop 1
	v_add_f32_dpp v112, v114, v114 quad_perm:[1,0,3,2] row_mask:0xf bank_mask:0xf
	s_nop 1
	v_add_f32_dpp v112, v112, v112 quad_perm:[2,3,0,1] row_mask:0xf bank_mask:0xf
	s_nop 1
	v_add_f32_dpp v112, v112, v112 row_half_mirror row_mask:0xf bank_mask:0xf
	s_nop 1
	v_add_f32_dpp v112, v112, v112 row_mirror row_mask:0xf bank_mask:0xf
	s_nop 1
	v_add_f32_dpp v112, v112, v112 row_bcast:15 row_mask:0xa bank_mask:0xf
	s_nop 1
	v_add_f32_dpp v112, v112, v112 row_bcast:31 row_mask:0xc bank_mask:0xf
	s_nop 1
	v_readlane_b32 s14, v112, 63
	s_nop 3
	v_fma_f32 v118, s14, v122, v123
	v_rsq_f32_e32 v118, v118
	s_nop 0
	v_pk_mul_f32 v[32:33], v[32:33], v[118:119] op_sel_hi:[1,0]
	v_pk_mul_f32 v[34:35], v[34:35], v[118:119] op_sel_hi:[1,0]
	v_pk_mul_f32 v[36:37], v[36:37], v[118:119] op_sel_hi:[1,0]
	v_pk_mul_f32 v[38:39], v[38:39], v[118:119] op_sel_hi:[1,0]
	v_pk_mul_f32 v[40:41], v[40:41], v[118:119] op_sel_hi:[1,0]
	v_pk_mul_f32 v[42:43], v[42:43], v[118:119] op_sel_hi:[1,0]
	v_pk_mul_f32 v[44:45], v[44:45], v[118:119] op_sel_hi:[1,0]
	v_pk_mul_f32 v[46:47], v[46:47], v[118:119] op_sel_hi:[1,0]
	v_pk_fma_f32 v[32:33], v[32:33], v[0:1], v[16:17]
	v_pk_fma_f32 v[34:35], v[34:35], v[2:3], v[18:19]
	v_pk_fma_f32 v[36:37], v[36:37], v[4:5], v[20:21]
	v_pk_fma_f32 v[38:39], v[38:39], v[6:7], v[22:23]
	v_pk_fma_f32 v[40:41], v[40:41], v[8:9], v[24:25]
	v_pk_fma_f32 v[42:43], v[42:43], v[10:11], v[26:27]
	v_pk_fma_f32 v[44:45], v[44:45], v[12:13], v[28:29]
	v_pk_fma_f32 v[46:47], v[46:47], v[14:15], v[30:31]
	v_cvt_pk_bf16_f32 v96, v32, v33
	v_cvt_pk_bf16_f32 v97, v34, v35
	v_cvt_pk_bf16_f32 v98, v36, v37
	v_cvt_pk_bf16_f32 v99, v38, v39
	v_cvt_pk_bf16_f32 v100, v40, v41
	v_cvt_pk_bf16_f32 v101, v42, v43
	v_cvt_pk_bf16_f32 v102, v44, v45
	v_cvt_pk_bf16_f32 v103, v46, v47
	global_store_dwordx2 v121, v[96:97], s[6:7] offset:0
	global_store_dwordx2 v121, v[98:99], s[6:7] offset:512
	global_store_dwordx2 v121, v[100:101], s[6:7] offset:1024
	global_store_dwordx2 v121, v[102:103], s[6:7] offset:1536
	s_add_u32 s6, s6, 0x800
	s_addc_u32 s7, s7, 0
	global_load_dwordx4 v[32:35], v120, s[4:5] offset:0
	global_load_dwordx4 v[36:39], v120, s[4:5] offset:1024
	global_load_dwordx4 v[40:43], v120, s[4:5] offset:2048
	global_load_dwordx4 v[44:47], v120, s[4:5] offset:3072
	s_add_u32 s4, s4, 0x1000
	s_addc_u32 s5, s5, 0
	s_waitcnt vmcnt(24)
	v_pk_add_f32 v[96:97], v[48:49], v[50:51]
	v_pk_add_f32 v[96:97], v[96:97], v[52:53]
	v_pk_add_f32 v[96:97], v[96:97], v[54:55]
	v_pk_add_f32 v[96:97], v[96:97], v[56:57]
	v_pk_add_f32 v[96:97], v[96:97], v[58:59]
	v_pk_add_f32 v[96:97], v[96:97], v[60:61]
	v_pk_add_f32 v[96:97], v[96:97], v[62:63]
	v_add_f32_e32 v114, v96, v97
	s_nop 1
	v_add_f32_dpp v112, v114, v114 quad_perm:[1,0,3,2] row_mask:0xf bank_mask:0xf
	s_nop 1
	v_add_f32_dpp v112, v112, v112 quad_perm:[2,3,0,1] row_mask:0xf bank_mask:0xf
	s_nop 1
	v_add_f32_dpp v112, v112, v112 row_half_mirror row_mask:0xf bank_mask:0xf
	s_nop 1
	v_add_f32_dpp v112, v112, v112 row_mirror row_mask:0xf bank_mask:0xf
	s_nop 1
	v_add_f32_dpp v112, v112, v112 row_bcast:15 row_mask:0xa bank_mask:0xf
	s_nop 1
	v_add_f32_dpp v112, v112, v112 row_bcast:31 row_mask:0xc bank_mask:0xf
	s_nop 1
	v_readlane_b32 s14, v112, 63
	s_nop 3
	s_mov_b32 s15, s14
	v_pk_fma_f32 v[48:49], s[14:15], v[116:117], v[48:49]
	v_pk_fma_f32 v[50:51], s[14:15], v[116:117], v[50:51]
	v_pk_fma_f32 v[52:53], s[14:15], v[116:117], v[52:53]
	v_pk_fma_f32 v[54:55], s[14:15], v[116:117], v[54:55]
	v_pk_fma_f32 v[56:57], s[14:15], v[116:117], v[56:57]
	v_pk_fma_f32 v[58:59], s[14:15], v[116:117], v[58:59]
	v_pk_fma_f32 v[60:61], s[14:15], v[116:117], v[60:61]
	v_pk_fma_f32 v[62:63], s[14:15], v[116:117], v[62:63]
	v_pk_mul_f32 v[96:97], v[48:49], v[48:49]
	v_pk_fma_f32 v[96:97], v[50:51], v[50:51], v[96:97]
	v_pk_fma_f32 v[96:97], v[52:53], v[52:53], v[96:97]
	v_pk_fma_f32 v[96:97], v[54:55], v[54:55], v[96:97]
	v_pk_fma_f32 v[96:97], v[56:57], v[56:57], v[96:97]
	v_pk_fma_f32 v[96:97], v[58:59], v[58:59], v[96:97]
	v_pk_fma_f32 v[96:97], v[60:61], v[60:61], v[96:97]
	v_pk_fma_f32 v[96:97], v[62:63], v[62:63], v[96:97]
	v_add_f32_e32 v114, v96, v97
	s_nop 1
	v_add_f32_dpp v112, v114, v114 quad_perm:[1,0,3,2] row_mask:0xf bank_mask:0xf
	s_nop 1
	v_add_f32_dpp v112, v112, v112 quad_perm:[2,3,0,1] row_mask:0xf bank_mask:0xf
	s_nop 1
	v_add_f32_dpp v112, v112, v112 row_half_mirror row_mask:0xf bank_mask:0xf
	s_nop 1
	v_add_f32_dpp v112, v112, v112 row_mirror row_mask:0xf bank_mask:0xf
	s_nop 1
	v_add_f32_dpp v112, v112, v112 row_bcast:15 row_mask:0xa bank_mask:0xf
	s_nop 1
	v_add_f32_dpp v112, v112, v112 row_bcast:31 row_mask:0xc bank_mask:0xf
	s_nop 1
	v_readlane_b32 s14, v112, 63
	s_nop 3
	v_fma_f32 v118, s14, v122, v123
	v_rsq_f32_e32 v118, v118
	s_nop 0
	v_pk_mul_f32 v[48:49], v[48:49], v[118:119] op_sel_hi:[1,0]
	v_pk_mul_f32 v[50:51], v[50:51], v[118:119] op_sel_hi:[1,0]
	v_pk_mul_f32 v[52:53], v[52:53], v[118:119] op_sel_hi:[1,0]
	v_pk_mul_f32 v[54:55], v[54:55], v[118:119] op_sel_hi:[1,0]
	v_pk_mul_f32 v[56:57], v[56:57], v[118:119] op_sel_hi:[1,0]
	v_pk_mul_f32 v[58:59], v[58:59], v[118:119] op_sel_hi:[1,0]
	v_pk_mul_f32 v[60:61], v[60:61], v[118:119] op_sel_hi:[1,0]
	v_pk_mul_f32 v[62:63], v[62:63], v[118:119] op_sel_hi:[1,0]
	v_pk_fma_f32 v[48:49], v[48:49], v[0:1], v[16:17]
	v_pk_fma_f32 v[50:51], v[50:51], v[2:3], v[18:19]
	v_pk_fma_f32 v[52:53], v[52:53], v[4:5], v[20:21]
	v_pk_fma_f32 v[54:55], v[54:55], v[6:7], v[22:23]
	v_pk_fma_f32 v[56:57], v[56:57], v[8:9], v[24:25]
	v_pk_fma_f32 v[58:59], v[58:59], v[10:11], v[26:27]
	v_pk_fma_f32 v[60:61], v[60:61], v[12:13], v[28:29]
	v_pk_fma_f32 v[62:63], v[62:63], v[14:15], v[30:31]
	v_cvt_pk_bf16_f32 v96, v48, v49
	v_cvt_pk_bf16_f32 v97, v50, v51
	v_cvt_pk_bf16_f32 v98, v52, v53
	v_cvt_pk_bf16_f32 v99, v54, v55
	v_cvt_pk_bf16_f32 v100, v56, v57
	v_cvt_pk_bf16_f32 v101, v58, v59
	v_cvt_pk_bf16_f32 v102, v60, v61
	v_cvt_pk_bf16_f32 v103, v62, v63
	global_store_dwordx2 v121, v[96:97], s[6:7] offset:0
	global_store_dwordx2 v121, v[98:99], s[6:7] offset:512
	global_store_dwordx2 v121, v[100:101], s[6:7] offset:1024
	global_store_dwordx2 v121, v[102:103], s[6:7] offset:1536
	s_add_u32 s6, s6, 0x800
	s_addc_u32 s7, s7, 0
	global_load_dwordx4 v[48:51], v120, s[4:5] offset:0
	global_load_dwordx4 v[52:55], v120, s[4:5] offset:1024
	global_load_dwordx4 v[56:59], v120, s[4:5] offset:2048
	global_load_dwordx4 v[60:63], v120, s[4:5] offset:3072
	s_add_u32 s4, s4, 0x1000
	s_addc_u32 s5, s5, 0
	s_waitcnt vmcnt(24)
	v_pk_add_f32 v[96:97], v[64:65], v[66:67]
	v_pk_add_f32 v[96:97], v[96:97], v[68:69]
	v_pk_add_f32 v[96:97], v[96:97], v[70:71]
	v_pk_add_f32 v[96:97], v[96:97], v[72:73]
	v_pk_add_f32 v[96:97], v[96:97], v[74:75]
	v_pk_add_f32 v[96:97], v[96:97], v[76:77]
	v_pk_add_f32 v[96:97], v[96:97], v[78:79]
	v_add_f32_e32 v114, v96, v97
	s_nop 1
	v_add_f32_dpp v112, v114, v114 quad_perm:[1,0,3,2] row_mask:0xf bank_mask:0xf
	s_nop 1
	v_add_f32_dpp v112, v112, v112 quad_perm:[2,3,0,1] row_mask:0xf bank_mask:0xf
	s_nop 1
	v_add_f32_dpp v112, v112, v112 row_half_mirror row_mask:0xf bank_mask:0xf
	s_nop 1
	v_add_f32_dpp v112, v112, v112 row_mirror row_mask:0xf bank_mask:0xf
	s_nop 1
	v_add_f32_dpp v112, v112, v112 row_bcast:15 row_mask:0xa bank_mask:0xf
	s_nop 1
	v_add_f32_dpp v112, v112, v112 row_bcast:31 row_mask:0xc bank_mask:0xf
	s_nop 1
	v_readlane_b32 s14, v112, 63
	s_nop 3
	s_mov_b32 s15, s14
	v_pk_fma_f32 v[64:65], s[14:15], v[116:117], v[64:65]
	v_pk_fma_f32 v[66:67], s[14:15], v[116:117], v[66:67]
	v_pk_fma_f32 v[68:69], s[14:15], v[116:117], v[68:69]
	v_pk_fma_f32 v[70:71], s[14:15], v[116:117], v[70:71]
	v_pk_fma_f32 v[72:73], s[14:15], v[116:117], v[72:73]
	v_pk_fma_f32 v[74:75], s[14:15], v[116:117], v[74:75]
	v_pk_fma_f32 v[76:77], s[14:15], v[116:117], v[76:77]
	v_pk_fma_f32 v[78:79], s[14:15], v[116:117], v[78:79]
	v_pk_mul_f32 v[96:97], v[64:65], v[64:65]
	v_pk_fma_f32 v[96:97], v[66:67], v[66:67], v[96:97]
	v_pk_fma_f32 v[96:97], v[68:69], v[68:69], v[96:97]
	v_pk_fma_f32 v[96:97], v[70:71], v[70:71], v[96:97]
	v_pk_fma_f32 v[96:97], v[72:73], v[72:73], v[96:97]
	v_pk_fma_f32 v[96:97], v[74:75], v[74:75], v[96:97]
	v_pk_fma_f32 v[96:97], v[76:77], v[76:77], v[96:97]
	v_pk_fma_f32 v[96:97], v[78:79], v[78:79], v[96:97]
	v_add_f32_e32 v114, v96, v97
	s_nop 1
	v_add_f32_dpp v112, v114, v114 quad_perm:[1,0,3,2] row_mask:0xf bank_mask:0xf
	s_nop 1
	v_add_f32_dpp v112, v112, v112 quad_perm:[2,3,0,1] row_mask:0xf bank_mask:0xf
	s_nop 1
	v_add_f32_dpp v112, v112, v112 row_half_mirror row_mask:0xf bank_mask:0xf
	s_nop 1
	v_add_f32_dpp v112, v112, v112 row_mirror row_mask:0xf bank_mask:0xf
	s_nop 1
	v_add_f32_dpp v112, v112, v112 row_bcast:15 row_mask:0xa bank_mask:0xf
	s_nop 1
	v_add_f32_dpp v112, v112, v112 row_bcast:31 row_mask:0xc bank_mask:0xf
	s_nop 1
	v_readlane_b32 s14, v112, 63
	s_nop 3
	v_fma_f32 v118, s14, v122, v123
	v_rsq_f32_e32 v118, v118
	s_nop 0
	v_pk_mul_f32 v[64:65], v[64:65], v[118:119] op_sel_hi:[1,0]
	v_pk_mul_f32 v[66:67], v[66:67], v[118:119] op_sel_hi:[1,0]
	v_pk_mul_f32 v[68:69], v[68:69], v[118:119] op_sel_hi:[1,0]
	v_pk_mul_f32 v[70:71], v[70:71], v[118:119] op_sel_hi:[1,0]
	v_pk_mul_f32 v[72:73], v[72:73], v[118:119] op_sel_hi:[1,0]
	v_pk_mul_f32 v[74:75], v[74:75], v[118:119] op_sel_hi:[1,0]
	v_pk_mul_f32 v[76:77], v[76:77], v[118:119] op_sel_hi:[1,0]
	v_pk_mul_f32 v[78:79], v[78:79], v[118:119] op_sel_hi:[1,0]
	v_pk_fma_f32 v[64:65], v[64:65], v[0:1], v[16:17]
	v_pk_fma_f32 v[66:67], v[66:67], v[2:3], v[18:19]
	v_pk_fma_f32 v[68:69], v[68:69], v[4:5], v[20:21]
	v_pk_fma_f32 v[70:71], v[70:71], v[6:7], v[22:23]
	v_pk_fma_f32 v[72:73], v[72:73], v[8:9], v[24:25]
	v_pk_fma_f32 v[74:75], v[74:75], v[10:11], v[26:27]
	v_pk_fma_f32 v[76:77], v[76:77], v[12:13], v[28:29]
	v_pk_fma_f32 v[78:79], v[78:79], v[14:15], v[30:31]
	v_cvt_pk_bf16_f32 v96, v64, v65
	v_cvt_pk_bf16_f32 v97, v66, v67
	v_cvt_pk_bf16_f32 v98, v68, v69
	v_cvt_pk_bf16_f32 v99, v70, v71
	v_cvt_pk_bf16_f32 v100, v72, v73
	v_cvt_pk_bf16_f32 v101, v74, v75
	v_cvt_pk_bf16_f32 v102, v76, v77
	v_cvt_pk_bf16_f32 v103, v78, v79
	global_store_dwordx2 v121, v[96:97], s[6:7] offset:0
	global_store_dwordx2 v121, v[98:99], s[6:7] offset:512
	global_store_dwordx2 v121, v[100:101], s[6:7] offset:1024
	global_store_dwordx2 v121, v[102:103], s[6:7] offset:1536
	s_add_u32 s6, s6, 0x800
	s_addc_u32 s7, s7, 0
	global_load_dwordx4 v[64:67], v120, s[4:5] offset:0
	global_load_dwordx4 v[68:71], v120, s[4:5] offset:1024
	global_load_dwordx4 v[72:75], v120, s[4:5] offset:2048
	global_load_dwordx4 v[76:79], v120, s[4:5] offset:3072
	s_add_u32 s4, s4, 0x1000
	s_addc_u32 s5, s5, 0
	s_waitcnt vmcnt(24)
	v_pk_add_f32 v[96:97], v[80:81], v[82:83]
	v_pk_add_f32 v[96:97], v[96:97], v[84:85]
	v_pk_add_f32 v[96:97], v[96:97], v[86:87]
	v_pk_add_f32 v[96:97], v[96:97], v[88:89]
	v_pk_add_f32 v[96:97], v[96:97], v[90:91]
	v_pk_add_f32 v[96:97], v[96:97], v[92:93]
	v_pk_add_f32 v[96:97], v[96:97], v[94:95]
	v_add_f32_e32 v114, v96, v97
	s_nop 1
	v_add_f32_dpp v112, v114, v114 quad_perm:[1,0,3,2] row_mask:0xf bank_mask:0xf
	s_nop 1
	v_add_f32_dpp v112, v112, v112 quad_perm:[2,3,0,1] row_mask:0xf bank_mask:0xf
	s_nop 1
	v_add_f32_dpp v112, v112, v112 row_half_mirror row_mask:0xf bank_mask:0xf
	s_nop 1
	v_add_f32_dpp v112, v112, v112 row_mirror row_mask:0xf bank_mask:0xf
	s_nop 1
	v_add_f32_dpp v112, v112, v112 row_bcast:15 row_mask:0xa bank_mask:0xf
	s_nop 1
	v_add_f32_dpp v112, v112, v112 row_bcast:31 row_mask:0xc bank_mask:0xf
	s_nop 1
	v_readlane_b32 s14, v112, 63
	s_nop 3
	s_mov_b32 s15, s14
	v_pk_fma_f32 v[80:81], s[14:15], v[116:117], v[80:81]
	v_pk_fma_f32 v[82:83], s[14:15], v[116:117], v[82:83]
	v_pk_fma_f32 v[84:85], s[14:15], v[116:117], v[84:85]
	v_pk_fma_f32 v[86:87], s[14:15], v[116:117], v[86:87]
	v_pk_fma_f32 v[88:89], s[14:15], v[116:117], v[88:89]
	v_pk_fma_f32 v[90:91], s[14:15], v[116:117], v[90:91]
	v_pk_fma_f32 v[92:93], s[14:15], v[116:117], v[92:93]
	v_pk_fma_f32 v[94:95], s[14:15], v[116:117], v[94:95]
	v_pk_mul_f32 v[96:97], v[80:81], v[80:81]
	v_pk_fma_f32 v[96:97], v[82:83], v[82:83], v[96:97]
	v_pk_fma_f32 v[96:97], v[84:85], v[84:85], v[96:97]
	v_pk_fma_f32 v[96:97], v[86:87], v[86:87], v[96:97]
	v_pk_fma_f32 v[96:97], v[88:89], v[88:89], v[96:97]
	v_pk_fma_f32 v[96:97], v[90:91], v[90:91], v[96:97]
	v_pk_fma_f32 v[96:97], v[92:93], v[92:93], v[96:97]
	v_pk_fma_f32 v[96:97], v[94:95], v[94:95], v[96:97]
	v_add_f32_e32 v114, v96, v97
	s_nop 1
	v_add_f32_dpp v112, v114, v114 quad_perm:[1,0,3,2] row_mask:0xf bank_mask:0xf
	s_nop 1
	v_add_f32_dpp v112, v112, v112 quad_perm:[2,3,0,1] row_mask:0xf bank_mask:0xf
	s_nop 1
	v_add_f32_dpp v112, v112, v112 row_half_mirror row_mask:0xf bank_mask:0xf
	s_nop 1
	v_add_f32_dpp v112, v112, v112 row_mirror row_mask:0xf bank_mask:0xf
	s_nop 1
	v_add_f32_dpp v112, v112, v112 row_bcast:15 row_mask:0xa bank_mask:0xf
	s_nop 1
	v_add_f32_dpp v112, v112, v112 row_bcast:31 row_mask:0xc bank_mask:0xf
	s_nop 1
	v_readlane_b32 s14, v112, 63
	s_nop 3
	v_fma_f32 v118, s14, v122, v123
	v_rsq_f32_e32 v118, v118
	s_nop 0
	v_pk_mul_f32 v[80:81], v[80:81], v[118:119] op_sel_hi:[1,0]
	v_pk_mul_f32 v[82:83], v[82:83], v[118:119] op_sel_hi:[1,0]
	v_pk_mul_f32 v[84:85], v[84:85], v[118:119] op_sel_hi:[1,0]
	v_pk_mul_f32 v[86:87], v[86:87], v[118:119] op_sel_hi:[1,0]
	v_pk_mul_f32 v[88:89], v[88:89], v[118:119] op_sel_hi:[1,0]
	v_pk_mul_f32 v[90:91], v[90:91], v[118:119] op_sel_hi:[1,0]
	v_pk_mul_f32 v[92:93], v[92:93], v[118:119] op_sel_hi:[1,0]
	v_pk_mul_f32 v[94:95], v[94:95], v[118:119] op_sel_hi:[1,0]
	v_pk_fma_f32 v[80:81], v[80:81], v[0:1], v[16:17]
	v_pk_fma_f32 v[82:83], v[82:83], v[2:3], v[18:19]
	v_pk_fma_f32 v[84:85], v[84:85], v[4:5], v[20:21]
	v_pk_fma_f32 v[86:87], v[86:87], v[6:7], v[22:23]
	v_pk_fma_f32 v[88:89], v[88:89], v[8:9], v[24:25]
	v_pk_fma_f32 v[90:91], v[90:91], v[10:11], v[26:27]
	v_pk_fma_f32 v[92:93], v[92:93], v[12:13], v[28:29]
	v_pk_fma_f32 v[94:95], v[94:95], v[14:15], v[30:31]
	v_cvt_pk_bf16_f32 v96, v80, v81
	v_cvt_pk_bf16_f32 v97, v82, v83
	v_cvt_pk_bf16_f32 v98, v84, v85
	v_cvt_pk_bf16_f32 v99, v86, v87
	v_cvt_pk_bf16_f32 v100, v88, v89
	v_cvt_pk_bf16_f32 v101, v90, v91
	v_cvt_pk_bf16_f32 v102, v92, v93
	v_cvt_pk_bf16_f32 v103, v94, v95
	global_store_dwordx2 v121, v[96:97], s[6:7] offset:0
	global_store_dwordx2 v121, v[98:99], s[6:7] offset:512
	global_store_dwordx2 v121, v[100:101], s[6:7] offset:1024
	global_store_dwordx2 v121, v[102:103], s[6:7] offset:1536
	s_add_u32 s6, s6, 0x800
	s_addc_u32 s7, s7, 0
	global_load_dwordx4 v[80:83], v120, s[4:5] offset:0
	global_load_dwordx4 v[84:87], v120, s[4:5] offset:1024
	global_load_dwordx4 v[88:91], v120, s[4:5] offset:2048
	global_load_dwordx4 v[92:95], v120, s[4:5] offset:3072
	s_add_u32 s4, s4, 0x1000
	s_addc_u32 s5, s5, 0
	s_waitcnt vmcnt(24)
	v_pk_add_f32 v[96:97], v[32:33], v[34:35]
	v_pk_add_f32 v[96:97], v[96:97], v[36:37]
	v_pk_add_f32 v[96:97], v[96:97], v[38:39]
	v_pk_add_f32 v[96:97], v[96:97], v[40:41]
	v_pk_add_f32 v[96:97], v[96:97], v[42:43]
	v_pk_add_f32 v[96:97], v[96:97], v[44:45]
	v_pk_add_f32 v[96:97], v[96:97], v[46:47]
	v_add_f32_e32 v114, v96, v97
	s_nop 1
	v_add_f32_dpp v112, v114, v114 quad_perm:[1,0,3,2] row_mask:0xf bank_mask:0xf
	s_nop 1
	v_add_f32_dpp v112, v112, v112 quad_perm:[2,3,0,1] row_mask:0xf bank_mask:0xf
	s_nop 1
	v_add_f32_dpp v112, v112, v112 row_half_mirror row_mask:0xf bank_mask:0xf
	s_nop 1
	v_add_f32_dpp v112, v112, v112 row_mirror row_mask:0xf bank_mask:0xf
	s_nop 1
	v_add_f32_dpp v112, v112, v112 row_bcast:15 row_mask:0xa bank_mask:0xf
	s_nop 1
	v_add_f32_dpp v112, v112, v112 row_bcast:31 row_mask:0xc bank_mask:0xf
	s_nop 1
	v_readlane_b32 s14, v112, 63
	s_nop 3
	s_mov_b32 s15, s14
	v_pk_fma_f32 v[32:33], s[14:15], v[116:117], v[32:33]
	v_pk_fma_f32 v[34:35], s[14:15], v[116:117], v[34:35]
	v_pk_fma_f32 v[36:37], s[14:15], v[116:117], v[36:37]
	v_pk_fma_f32 v[38:39], s[14:15], v[116:117], v[38:39]
	v_pk_fma_f32 v[40:41], s[14:15], v[116:117], v[40:41]
	v_pk_fma_f32 v[42:43], s[14:15], v[116:117], v[42:43]
	v_pk_fma_f32 v[44:45], s[14:15], v[116:117], v[44:45]
	v_pk_fma_f32 v[46:47], s[14:15], v[116:117], v[46:47]
	v_pk_mul_f32 v[96:97], v[32:33], v[32:33]
	v_pk_fma_f32 v[96:97], v[34:35], v[34:35], v[96:97]
	v_pk_fma_f32 v[96:97], v[36:37], v[36:37], v[96:97]
	v_pk_fma_f32 v[96:97], v[38:39], v[38:39], v[96:97]
	v_pk_fma_f32 v[96:97], v[40:41], v[40:41], v[96:97]
	v_pk_fma_f32 v[96:97], v[42:43], v[42:43], v[96:97]
	v_pk_fma_f32 v[96:97], v[44:45], v[44:45], v[96:97]
	v_pk_fma_f32 v[96:97], v[46:47], v[46:47], v[96:97]
	v_add_f32_e32 v114, v96, v97
	s_nop 1
	v_add_f32_dpp v112, v114, v114 quad_perm:[1,0,3,2] row_mask:0xf bank_mask:0xf
	s_nop 1
	v_add_f32_dpp v112, v112, v112 quad_perm:[2,3,0,1] row_mask:0xf bank_mask:0xf
	s_nop 1
	v_add_f32_dpp v112, v112, v112 row_half_mirror row_mask:0xf bank_mask:0xf
	s_nop 1
	v_add_f32_dpp v112, v112, v112 row_mirror row_mask:0xf bank_mask:0xf
	s_nop 1
	v_add_f32_dpp v112, v112, v112 row_bcast:15 row_mask:0xa bank_mask:0xf
	s_nop 1
	v_add_f32_dpp v112, v112, v112 row_bcast:31 row_mask:0xc bank_mask:0xf
	s_nop 1
	v_readlane_b32 s14, v112, 63
	s_nop 3
	v_fma_f32 v118, s14, v122, v123
	v_rsq_f32_e32 v118, v118
	s_nop 0
	v_pk_mul_f32 v[32:33], v[32:33], v[118:119] op_sel_hi:[1,0]
	v_pk_mul_f32 v[34:35], v[34:35], v[118:119] op_sel_hi:[1,0]
	v_pk_mul_f32 v[36:37], v[36:37], v[118:119] op_sel_hi:[1,0]
	v_pk_mul_f32 v[38:39], v[38:39], v[118:119] op_sel_hi:[1,0]
	v_pk_mul_f32 v[40:41], v[40:41], v[118:119] op_sel_hi:[1,0]
	v_pk_mul_f32 v[42:43], v[42:43], v[118:119] op_sel_hi:[1,0]
	v_pk_mul_f32 v[44:45], v[44:45], v[118:119] op_sel_hi:[1,0]
	v_pk_mul_f32 v[46:47], v[46:47], v[118:119] op_sel_hi:[1,0]
	v_pk_fma_f32 v[32:33], v[32:33], v[0:1], v[16:17]
	v_pk_fma_f32 v[34:35], v[34:35], v[2:3], v[18:19]
	v_pk_fma_f32 v[36:37], v[36:37], v[4:5], v[20:21]
	v_pk_fma_f32 v[38:39], v[38:39], v[6:7], v[22:23]
	v_pk_fma_f32 v[40:41], v[40:41], v[8:9], v[24:25]
	v_pk_fma_f32 v[42:43], v[42:43], v[10:11], v[26:27]
	v_pk_fma_f32 v[44:45], v[44:45], v[12:13], v[28:29]
	v_pk_fma_f32 v[46:47], v[46:47], v[14:15], v[30:31]
	v_cvt_pk_bf16_f32 v96, v32, v33
	v_cvt_pk_bf16_f32 v97, v34, v35
	v_cvt_pk_bf16_f32 v98, v36, v37
	v_cvt_pk_bf16_f32 v99, v38, v39
	v_cvt_pk_bf16_f32 v100, v40, v41
	v_cvt_pk_bf16_f32 v101, v42, v43
	v_cvt_pk_bf16_f32 v102, v44, v45
	v_cvt_pk_bf16_f32 v103, v46, v47
	global_store_dwordx2 v121, v[96:97], s[6:7] offset:0
	global_store_dwordx2 v121, v[98:99], s[6:7] offset:512
	global_store_dwordx2 v121, v[100:101], s[6:7] offset:1024
	global_store_dwordx2 v121, v[102:103], s[6:7] offset:1536
	s_add_u32 s6, s6, 0x800
	s_addc_u32 s7, s7, 0
	s_waitcnt vmcnt(20)
	v_pk_add_f32 v[96:97], v[48:49], v[50:51]
	v_pk_add_f32 v[96:97], v[96:97], v[52:53]
	v_pk_add_f32 v[96:97], v[96:97], v[54:55]
	v_pk_add_f32 v[96:97], v[96:97], v[56:57]
	v_pk_add_f32 v[96:97], v[96:97], v[58:59]
	v_pk_add_f32 v[96:97], v[96:97], v[60:61]
	v_pk_add_f32 v[96:97], v[96:97], v[62:63]
	v_add_f32_e32 v114, v96, v97
	s_nop 1
	v_add_f32_dpp v112, v114, v114 quad_perm:[1,0,3,2] row_mask:0xf bank_mask:0xf
	s_nop 1
	v_add_f32_dpp v112, v112, v112 quad_perm:[2,3,0,1] row_mask:0xf bank_mask:0xf
	s_nop 1
	v_add_f32_dpp v112, v112, v112 row_half_mirror row_mask:0xf bank_mask:0xf
	s_nop 1
	v_add_f32_dpp v112, v112, v112 row_mirror row_mask:0xf bank_mask:0xf
	s_nop 1
	v_add_f32_dpp v112, v112, v112 row_bcast:15 row_mask:0xa bank_mask:0xf
	s_nop 1
	v_add_f32_dpp v112, v112, v112 row_bcast:31 row_mask:0xc bank_mask:0xf
	s_nop 1
	v_readlane_b32 s14, v112, 63
	s_nop 3
	s_mov_b32 s15, s14
	v_pk_fma_f32 v[48:49], s[14:15], v[116:117], v[48:49]
	v_pk_fma_f32 v[50:51], s[14:15], v[116:117], v[50:51]
	v_pk_fma_f32 v[52:53], s[14:15], v[116:117], v[52:53]
	v_pk_fma_f32 v[54:55], s[14:15], v[116:117], v[54:55]
	v_pk_fma_f32 v[56:57], s[14:15], v[116:117], v[56:57]
	v_pk_fma_f32 v[58:59], s[14:15], v[116:117], v[58:59]
	v_pk_fma_f32 v[60:61], s[14:15], v[116:117], v[60:61]
	v_pk_fma_f32 v[62:63], s[14:15], v[116:117], v[62:63]
	v_pk_mul_f32 v[96:97], v[48:49], v[48:49]
	v_pk_fma_f32 v[96:97], v[50:51], v[50:51], v[96:97]
	v_pk_fma_f32 v[96:97], v[52:53], v[52:53], v[96:97]
	v_pk_fma_f32 v[96:97], v[54:55], v[54:55], v[96:97]
	v_pk_fma_f32 v[96:97], v[56:57], v[56:57], v[96:97]
	v_pk_fma_f32 v[96:97], v[58:59], v[58:59], v[96:97]
	v_pk_fma_f32 v[96:97], v[60:61], v[60:61], v[96:97]
	v_pk_fma_f32 v[96:97], v[62:63], v[62:63], v[96:97]
	v_add_f32_e32 v114, v96, v97
	s_nop 1
	v_add_f32_dpp v112, v114, v114 quad_perm:[1,0,3,2] row_mask:0xf bank_mask:0xf
	s_nop 1
	v_add_f32_dpp v112, v112, v112 quad_perm:[2,3,0,1] row_mask:0xf bank_mask:0xf
	s_nop 1
	v_add_f32_dpp v112, v112, v112 row_half_mirror row_mask:0xf bank_mask:0xf
	s_nop 1
	v_add_f32_dpp v112, v112, v112 row_mirror row_mask:0xf bank_mask:0xf
	s_nop 1
	v_add_f32_dpp v112, v112, v112 row_bcast:15 row_mask:0xa bank_mask:0xf
	s_nop 1
	v_add_f32_dpp v112, v112, v112 row_bcast:31 row_mask:0xc bank_mask:0xf
	s_nop 1
	v_readlane_b32 s14, v112, 63
	s_nop 3
	v_fma_f32 v118, s14, v122, v123
	v_rsq_f32_e32 v118, v118
	s_nop 0
	v_pk_mul_f32 v[48:49], v[48:49], v[118:119] op_sel_hi:[1,0]
	v_pk_mul_f32 v[50:51], v[50:51], v[118:119] op_sel_hi:[1,0]
	v_pk_mul_f32 v[52:53], v[52:53], v[118:119] op_sel_hi:[1,0]
	v_pk_mul_f32 v[54:55], v[54:55], v[118:119] op_sel_hi:[1,0]
	v_pk_mul_f32 v[56:57], v[56:57], v[118:119] op_sel_hi:[1,0]
	v_pk_mul_f32 v[58:59], v[58:59], v[118:119] op_sel_hi:[1,0]
	v_pk_mul_f32 v[60:61], v[60:61], v[118:119] op_sel_hi:[1,0]
	v_pk_mul_f32 v[62:63], v[62:63], v[118:119] op_sel_hi:[1,0]
	v_pk_fma_f32 v[48:49], v[48:49], v[0:1], v[16:17]
	v_pk_fma_f32 v[50:51], v[50:51], v[2:3], v[18:19]
	v_pk_fma_f32 v[52:53], v[52:53], v[4:5], v[20:21]
	v_pk_fma_f32 v[54:55], v[54:55], v[6:7], v[22:23]
	v_pk_fma_f32 v[56:57], v[56:57], v[8:9], v[24:25]
	v_pk_fma_f32 v[58:59], v[58:59], v[10:11], v[26:27]
	v_pk_fma_f32 v[60:61], v[60:61], v[12:13], v[28:29]
	v_pk_fma_f32 v[62:63], v[62:63], v[14:15], v[30:31]
	v_cvt_pk_bf16_f32 v96, v48, v49
	v_cvt_pk_bf16_f32 v97, v50, v51
	v_cvt_pk_bf16_f32 v98, v52, v53
	v_cvt_pk_bf16_f32 v99, v54, v55
	v_cvt_pk_bf16_f32 v100, v56, v57
	v_cvt_pk_bf16_f32 v101, v58, v59
	v_cvt_pk_bf16_f32 v102, v60, v61
	v_cvt_pk_bf16_f32 v103, v62, v63
	global_store_dwordx2 v121, v[96:97], s[6:7] offset:0
	global_store_dwordx2 v121, v[98:99], s[6:7] offset:512
	global_store_dwordx2 v121, v[100:101], s[6:7] offset:1024
	global_store_dwordx2 v121, v[102:103], s[6:7] offset:1536
	s_add_u32 s6, s6, 0x800
	s_addc_u32 s7, s7, 0
	s_waitcnt vmcnt(16)
	v_pk_add_f32 v[96:97], v[64:65], v[66:67]
	v_pk_add_f32 v[96:97], v[96:97], v[68:69]
	v_pk_add_f32 v[96:97], v[96:97], v[70:71]
	v_pk_add_f32 v[96:97], v[96:97], v[72:73]
	v_pk_add_f32 v[96:97], v[96:97], v[74:75]
	v_pk_add_f32 v[96:97], v[96:97], v[76:77]
	v_pk_add_f32 v[96:97], v[96:97], v[78:79]
	v_add_f32_e32 v114, v96, v97
	s_nop 1
	v_add_f32_dpp v112, v114, v114 quad_perm:[1,0,3,2] row_mask:0xf bank_mask:0xf
	s_nop 1
	v_add_f32_dpp v112, v112, v112 quad_perm:[2,3,0,1] row_mask:0xf bank_mask:0xf
	s_nop 1
	v_add_f32_dpp v112, v112, v112 row_half_mirror row_mask:0xf bank_mask:0xf
	s_nop 1
	v_add_f32_dpp v112, v112, v112 row_mirror row_mask:0xf bank_mask:0xf
	s_nop 1
	v_add_f32_dpp v112, v112, v112 row_bcast:15 row_mask:0xa bank_mask:0xf
	s_nop 1
	v_add_f32_dpp v112, v112, v112 row_bcast:31 row_mask:0xc bank_mask:0xf
	s_nop 1
	v_readlane_b32 s14, v112, 63
	s_nop 3
	s_mov_b32 s15, s14
	v_pk_fma_f32 v[64:65], s[14:15], v[116:117], v[64:65]
	v_pk_fma_f32 v[66:67], s[14:15], v[116:117], v[66:67]
	v_pk_fma_f32 v[68:69], s[14:15], v[116:117], v[68:69]
	v_pk_fma_f32 v[70:71], s[14:15], v[116:117], v[70:71]
	v_pk_fma_f32 v[72:73], s[14:15], v[116:117], v[72:73]
	v_pk_fma_f32 v[74:75], s[14:15], v[116:117], v[74:75]
	v_pk_fma_f32 v[76:77], s[14:15], v[116:117], v[76:77]
	v_pk_fma_f32 v[78:79], s[14:15], v[116:117], v[78:79]
	v_pk_mul_f32 v[96:97], v[64:65], v[64:65]
	v_pk_fma_f32 v[96:97], v[66:67], v[66:67], v[96:97]
	v_pk_fma_f32 v[96:97], v[68:69], v[68:69], v[96:97]
	v_pk_fma_f32 v[96:97], v[70:71], v[70:71], v[96:97]
	v_pk_fma_f32 v[96:97], v[72:73], v[72:73], v[96:97]
	v_pk_fma_f32 v[96:97], v[74:75], v[74:75], v[96:97]
	v_pk_fma_f32 v[96:97], v[76:77], v[76:77], v[96:97]
	v_pk_fma_f32 v[96:97], v[78:79], v[78:79], v[96:97]
	v_add_f32_e32 v114, v96, v97
	s_nop 1
	v_add_f32_dpp v112, v114, v114 quad_perm:[1,0,3,2] row_mask:0xf bank_mask:0xf
	s_nop 1
	v_add_f32_dpp v112, v112, v112 quad_perm:[2,3,0,1] row_mask:0xf bank_mask:0xf
	s_nop 1
	v_add_f32_dpp v112, v112, v112 row_half_mirror row_mask:0xf bank_mask:0xf
	s_nop 1
	v_add_f32_dpp v112, v112, v112 row_mirror row_mask:0xf bank_mask:0xf
	s_nop 1
	v_add_f32_dpp v112, v112, v112 row_bcast:15 row_mask:0xa bank_mask:0xf
	s_nop 1
	v_add_f32_dpp v112, v112, v112 row_bcast:31 row_mask:0xc bank_mask:0xf
	s_nop 1
	v_readlane_b32 s14, v112, 63
	s_nop 3
	v_fma_f32 v118, s14, v122, v123
	v_rsq_f32_e32 v118, v118
	s_nop 0
	v_pk_mul_f32 v[64:65], v[64:65], v[118:119] op_sel_hi:[1,0]
	v_pk_mul_f32 v[66:67], v[66:67], v[118:119] op_sel_hi:[1,0]
	v_pk_mul_f32 v[68:69], v[68:69], v[118:119] op_sel_hi:[1,0]
	v_pk_mul_f32 v[70:71], v[70:71], v[118:119] op_sel_hi:[1,0]
	v_pk_mul_f32 v[72:73], v[72:73], v[118:119] op_sel_hi:[1,0]
	v_pk_mul_f32 v[74:75], v[74:75], v[118:119] op_sel_hi:[1,0]
	v_pk_mul_f32 v[76:77], v[76:77], v[118:119] op_sel_hi:[1,0]
	v_pk_mul_f32 v[78:79], v[78:79], v[118:119] op_sel_hi:[1,0]
	v_pk_fma_f32 v[64:65], v[64:65], v[0:1], v[16:17]
	v_pk_fma_f32 v[66:67], v[66:67], v[2:3], v[18:19]
	v_pk_fma_f32 v[68:69], v[68:69], v[4:5], v[20:21]
	v_pk_fma_f32 v[70:71], v[70:71], v[6:7], v[22:23]
	v_pk_fma_f32 v[72:73], v[72:73], v[8:9], v[24:25]
	v_pk_fma_f32 v[74:75], v[74:75], v[10:11], v[26:27]
	v_pk_fma_f32 v[76:77], v[76:77], v[12:13], v[28:29]
	v_pk_fma_f32 v[78:79], v[78:79], v[14:15], v[30:31]
	v_cvt_pk_bf16_f32 v96, v64, v65
	v_cvt_pk_bf16_f32 v97, v66, v67
	v_cvt_pk_bf16_f32 v98, v68, v69
	v_cvt_pk_bf16_f32 v99, v70, v71
	v_cvt_pk_bf16_f32 v100, v72, v73
	v_cvt_pk_bf16_f32 v101, v74, v75
	v_cvt_pk_bf16_f32 v102, v76, v77
	v_cvt_pk_bf16_f32 v103, v78, v79
	global_store_dwordx2 v121, v[96:97], s[6:7] offset:0
	global_store_dwordx2 v121, v[98:99], s[6:7] offset:512
	global_store_dwordx2 v121, v[100:101], s[6:7] offset:1024
	global_store_dwordx2 v121, v[102:103], s[6:7] offset:1536
	s_add_u32 s6, s6, 0x800
	s_addc_u32 s7, s7, 0
	s_waitcnt vmcnt(12)
	v_pk_add_f32 v[96:97], v[80:81], v[82:83]
	v_pk_add_f32 v[96:97], v[96:97], v[84:85]
	v_pk_add_f32 v[96:97], v[96:97], v[86:87]
	v_pk_add_f32 v[96:97], v[96:97], v[88:89]
	v_pk_add_f32 v[96:97], v[96:97], v[90:91]
	v_pk_add_f32 v[96:97], v[96:97], v[92:93]
	v_pk_add_f32 v[96:97], v[96:97], v[94:95]
	v_add_f32_e32 v114, v96, v97
	s_nop 1
	v_add_f32_dpp v112, v114, v114 quad_perm:[1,0,3,2] row_mask:0xf bank_mask:0xf
	s_nop 1
	v_add_f32_dpp v112, v112, v112 quad_perm:[2,3,0,1] row_mask:0xf bank_mask:0xf
	s_nop 1
	v_add_f32_dpp v112, v112, v112 row_half_mirror row_mask:0xf bank_mask:0xf
	s_nop 1
	v_add_f32_dpp v112, v112, v112 row_mirror row_mask:0xf bank_mask:0xf
	s_nop 1
	v_add_f32_dpp v112, v112, v112 row_bcast:15 row_mask:0xa bank_mask:0xf
	s_nop 1
	v_add_f32_dpp v112, v112, v112 row_bcast:31 row_mask:0xc bank_mask:0xf
	s_nop 1
	v_readlane_b32 s14, v112, 63
	s_nop 3
	s_mov_b32 s15, s14
	v_pk_fma_f32 v[80:81], s[14:15], v[116:117], v[80:81]
	v_pk_fma_f32 v[82:83], s[14:15], v[116:117], v[82:83]
	v_pk_fma_f32 v[84:85], s[14:15], v[116:117], v[84:85]
	v_pk_fma_f32 v[86:87], s[14:15], v[116:117], v[86:87]
	v_pk_fma_f32 v[88:89], s[14:15], v[116:117], v[88:89]
	v_pk_fma_f32 v[90:91], s[14:15], v[116:117], v[90:91]
	v_pk_fma_f32 v[92:93], s[14:15], v[116:117], v[92:93]
	v_pk_fma_f32 v[94:95], s[14:15], v[116:117], v[94:95]
	v_pk_mul_f32 v[96:97], v[80:81], v[80:81]
	v_pk_fma_f32 v[96:97], v[82:83], v[82:83], v[96:97]
	v_pk_fma_f32 v[96:97], v[84:85], v[84:85], v[96:97]
	v_pk_fma_f32 v[96:97], v[86:87], v[86:87], v[96:97]
	v_pk_fma_f32 v[96:97], v[88:89], v[88:89], v[96:97]
	v_pk_fma_f32 v[96:97], v[90:91], v[90:91], v[96:97]
	v_pk_fma_f32 v[96:97], v[92:93], v[92:93], v[96:97]
	v_pk_fma_f32 v[96:97], v[94:95], v[94:95], v[96:97]
	v_add_f32_e32 v114, v96, v97
	s_nop 1
	v_add_f32_dpp v112, v114, v114 quad_perm:[1,0,3,2] row_mask:0xf bank_mask:0xf
	s_nop 1
	v_add_f32_dpp v112, v112, v112 quad_perm:[2,3,0,1] row_mask:0xf bank_mask:0xf
	s_nop 1
	v_add_f32_dpp v112, v112, v112 row_half_mirror row_mask:0xf bank_mask:0xf
	s_nop 1
	v_add_f32_dpp v112, v112, v112 row_mirror row_mask:0xf bank_mask:0xf
	s_nop 1
	v_add_f32_dpp v112, v112, v112 row_bcast:15 row_mask:0xa bank_mask:0xf
	s_nop 1
	v_add_f32_dpp v112, v112, v112 row_bcast:31 row_mask:0xc bank_mask:0xf
	s_nop 1
	v_readlane_b32 s14, v112, 63
	s_nop 3
	v_fma_f32 v118, s14, v122, v123
	v_rsq_f32_e32 v118, v118
	s_nop 0
	v_pk_mul_f32 v[80:81], v[80:81], v[118:119] op_sel_hi:[1,0]
	v_pk_mul_f32 v[82:83], v[82:83], v[118:119] op_sel_hi:[1,0]
	v_pk_mul_f32 v[84:85], v[84:85], v[118:119] op_sel_hi:[1,0]
	v_pk_mul_f32 v[86:87], v[86:87], v[118:119] op_sel_hi:[1,0]
	v_pk_mul_f32 v[88:89], v[88:89], v[118:119] op_sel_hi:[1,0]
	v_pk_mul_f32 v[90:91], v[90:91], v[118:119] op_sel_hi:[1,0]
	v_pk_mul_f32 v[92:93], v[92:93], v[118:119] op_sel_hi:[1,0]
	v_pk_mul_f32 v[94:95], v[94:95], v[118:119] op_sel_hi:[1,0]
	v_pk_fma_f32 v[80:81], v[80:81], v[0:1], v[16:17]
	v_pk_fma_f32 v[82:83], v[82:83], v[2:3], v[18:19]
	v_pk_fma_f32 v[84:85], v[84:85], v[4:5], v[20:21]
	v_pk_fma_f32 v[86:87], v[86:87], v[6:7], v[22:23]
	v_pk_fma_f32 v[88:89], v[88:89], v[8:9], v[24:25]
	v_pk_fma_f32 v[90:91], v[90:91], v[10:11], v[26:27]
	v_pk_fma_f32 v[92:93], v[92:93], v[12:13], v[28:29]
	v_pk_fma_f32 v[94:95], v[94:95], v[14:15], v[30:31]
	v_cvt_pk_bf16_f32 v96, v80, v81
	v_cvt_pk_bf16_f32 v97, v82, v83
	v_cvt_pk_bf16_f32 v98, v84, v85
	v_cvt_pk_bf16_f32 v99, v86, v87
	v_cvt_pk_bf16_f32 v100, v88, v89
	v_cvt_pk_bf16_f32 v101, v90, v91
	v_cvt_pk_bf16_f32 v102, v92, v93
	v_cvt_pk_bf16_f32 v103, v94, v95
	global_store_dwordx2 v121, v[96:97], s[6:7] offset:0
	global_store_dwordx2 v121, v[98:99], s[6:7] offset:512
	global_store_dwordx2 v121, v[100:101], s[6:7] offset:1024
	global_store_dwordx2 v121, v[102:103], s[6:7] offset:1536
	s_add_u32 s6, s6, 0x800
	s_addc_u32 s7, s7, 0
